# hand-written P1 shift-vector block (batched loads + DPP wave reductions), P0 weight-copy items rebalanced, island barrier fast path when island is on one XCD, P3 x loads pipelined + nt
# speedup vs baseline: 1.0215x; 1.0215x over previous
.LBB0_55:
	v_writelane_b32 v254, s79, 42
	v_writelane_b32 v254, s30, 44
	s_nop 1
	v_writelane_b32 v254, s31, 45
	v_writelane_b32 v254, s15, 27
	v_writelane_b32 v254, s77, 26
	v_writelane_b32 v254, s76, 25
	v_writelane_b32 v254, s74, 23
	s_nop 1
	v_writelane_b32 v254, s75, 24
	v_writelane_b32 v254, s73, 22
	v_writelane_b32 v254, s72, 21
	s_or_b64 exec, exec, s[6:7]
	v_readlane_b32 s0, v254, 8
	v_readlane_b32 s1, v254, 9
	s_add_u32 s6, s0, 0x1000000
	s_addc_u32 s7, s1, 0
	s_add_u32 s30, s0, 0x1b00000
	v_readlane_b32 s2, v254, 10
	s_addc_u32 s31, s1, 0
	v_readlane_b32 s3, v254, 11
	s_add_u32 s2, s0, 0x2100000
	s_addc_u32 s3, s1, 0
	v_writelane_b32 v254, s2, 28
	s_nop 1
	v_writelane_b32 v254, s3, 29
	s_add_u32 s2, s0, 0x2c00000
	s_addc_u32 s3, s1, 0
	s_add_u32 s20, s0, 0x3200000
	v_writelane_b32 v254, s2, 32
	s_addc_u32 s21, s1, 0
	s_nop 0
	v_writelane_b32 v254, s3, 33
	s_add_u32 s2, s0, 0x3700000
	s_addc_u32 s3, s1, 0
	s_add_u32 s18, s0, 0x3900000
	s_addc_u32 s19, s1, 0
	s_add_u32 s16, s0, 0x3a00000
	s_addc_u32 s17, s1, 0
	s_lshl_b32 s0, s71, 3
	s_addk_i32 s0, 0x380
	v_writelane_b32 v254, s2, 34
	s_and_b32 s0, s0, 0x7f8
	s_add_i32 s42, s69, s0
	s_movk_i32 s98, 0x90
	s_movk_i32 s99, 0x8ff
	s_mov_b32 s100, 0xfffffc80
	s_cmp_lt_u32 s42, 0x380
	s_cselect_b32 s98, 0x70, s98
	s_cselect_b32 s99, 0x283f, s99
	s_cselect_b32 s100, 0x900, s100
	s_add_i32 s42, s42, s100
	v_writelane_b32 v254, s3, 35
	v_writelane_b32 v254, s71, 20
	s_cmp_gt_u32 s42, s99
	s_cbranch_scc1 .LBB0_370
	s_mul_i32 s0, s69, 0x3e00
	s_add_i32 s10, s10, s0
	v_lshrrev_b32_e32 v23, 5, v81
	s_movk_i32 s0, 0x84
	v_mov_b32_e32 v2, 0x108
	v_mad_u32_u24 v27, v23, s0, v2
	v_mov_b32_e32 v2, 0x210
	v_mad_u32_u24 v20, v23, s0, v2
	v_mov_b32_e32 v2, 0x318
	v_mad_u32_u24 v21, v23, s0, v2
	v_mov_b32_e32 v2, 0x420
	v_mad_u32_u24 v72, v23, s0, v2
	v_mov_b32_e32 v2, 0x528
	v_mad_u32_u24 v73, v23, s0, v2
	v_mov_b32_e32 v2, 0x630
	v_mad_u32_u24 v74, v23, s0, v2
	v_mov_b32_e32 v2, 0x738
	v_mad_u32_u24 v34, v23, s0, v2
	v_mov_b32_e32 v2, 0x840
	v_mad_u32_u24 v75, v23, s0, v2
	v_mov_b32_e32 v2, 0x948
	v_mad_u32_u24 v76, v23, s0, v2
	v_mov_b32_e32 v2, 0xa50
	v_mad_u32_u24 v77, v23, s0, v2
	v_mov_b32_e32 v2, 0xb58
	v_mad_u32_u24 v78, v23, s0, v2
	v_mov_b32_e32 v2, 0xc60
	v_mad_u32_u24 v79, v23, s0, v2
	v_mov_b32_e32 v2, 0xd68
	v_mad_u32_u24 v41, v23, s0, v2
	v_mov_b32_e32 v2, 0xe70
	v_mad_u32_u24 v80, v23, s0, v2
	v_mov_b32_e32 v2, 0xf78
	v_mad_u32_u24 v82, v23, s0, v2
	v_mov_b32_e32 v2, 0x1080
	v_mad_u32_u24 v83, v23, s0, v2
	v_mov_b32_e32 v2, 0x1188
	v_mad_u32_u24 v84, v23, s0, v2
	v_mov_b32_e32 v2, 0x1290
	v_mad_u32_u24 v85, v23, s0, v2
	v_mov_b32_e32 v2, 0x1398
	v_mad_u32_u24 v48, v23, s0, v2
	v_lshlrev_b32_e32 v2, 3, v81
	v_lshrrev_b32_e32 v61, 3, v81
	v_and_b32_e32 v2, 56, v2
	v_mul_u32_u24_e32 v6, 0x84, v2
	v_lshlrev_b32_e32 v7, 2, v61
	v_and_b32_e32 v22, 31, v93
	v_add3_u32 v62, s10, v6, v7
	v_lshlrev_b32_e32 v6, 2, v81
	v_lshl_add_u32 v24, v22, 2, s10
	v_and_b32_e32 v10, 16, v6
	v_lshrrev_b32_e32 v6, 1, v93
	v_readlane_b32 s2, v254, 34
	v_mad_u32_u24 v25, v23, s0, v24
	v_lshlrev_b32_e32 v2, 1, v2
	v_mov_b32_e32 v3, 0
	v_and_b32_e32 v11, 12, v6
	v_and_b32_e32 v12, 3, v93
	v_lshlrev_b32_e32 v69, 5, v81
	s_movk_i32 s0, 0x400
	v_readlane_b32 s3, v254, 35
	v_or_b32_e32 v6, v10, v11
	v_and_or_b32 v67, v69, s0, v22
	v_lshl_add_u64 v[8:9], s[2:3], 0, v[2:3]
	v_or_b32_e32 v11, v12, v11
	s_movk_i32 s0, 0x880
	v_readlane_b32 s2, v254, 32
	v_readlane_b32 s1, v254, 21
	s_nop 3
	s_mov_b32 s1, s98
	v_or3_b32 v68, v11, v10, s0
	v_readlane_b32 s3, v254, 33
	v_readlane_b32 s0, v254, 18
	s_lshl_b32 s43, s1, 3
	v_or3_b32 v66, v6, v12, 64
	v_lshl_add_u64 v[12:13], s[2:3], 0, v[2:3]
	v_readlane_b32 s2, v254, 28
	s_bfe_u32 s0, s0, 0x20006
	v_readlane_b32 s3, v254, 29
	s_cmp_lt_u32 s0, 2
	v_writelane_b32 v254, s0, 36
	v_lshl_add_u64 v[16:17], s[2:3], 0, v[2:3]
	s_cselect_b64 s[2:3], -1, 0
	v_writelane_b32 v254, s2, 38
	s_bfe_u32 s0, s69, 0x10001
	s_lshl_b32 s46, s42, 5
	v_writelane_b32 v254, s3, 39
	v_writelane_b32 v254, s0, 40
	s_lshl_b32 s0, s42, 2
	s_add_i32 s64, s0, 0xffff6200
	s_lshl_b32 s0, s42, 11
	s_add_i32 s74, s0, 0xfed40000
	s_lshl_b32 s0, s42, 1
	v_or_b32_e32 v26, 2, v23
	v_or_b32_e32 v28, 4, v23
	v_or_b32_e32 v29, 6, v23
	v_or_b32_e32 v30, 8, v23
	v_or_b32_e32 v31, 10, v23
	v_or_b32_e32 v32, 12, v23
	v_or_b32_e32 v33, 14, v23
	v_or_b32_e32 v35, 16, v23
	v_or_b32_e32 v36, 18, v23
	v_or_b32_e32 v37, 20, v23
	v_or_b32_e32 v38, 22, v23
	v_or_b32_e32 v39, 24, v23
	v_or_b32_e32 v40, 26, v23
	v_or_b32_e32 v42, 28, v23
	v_or_b32_e32 v43, 30, v23
	v_or_b32_e32 v44, 32, v23
	v_or_b32_e32 v45, 34, v23
	v_or_b32_e32 v46, 36, v23
	v_or_b32_e32 v47, 38, v23
	v_or_b32_e32 v49, 40, v23
	v_or_b32_e32 v50, 42, v23
	v_or_b32_e32 v51, 44, v23
	v_or_b32_e32 v52, 46, v23
	v_or_b32_e32 v53, 48, v23
	v_or_b32_e32 v54, 50, v23
	v_or_b32_e32 v55, 52, v23
	v_or_b32_e32 v56, 54, v23
	v_or_b32_e32 v57, 56, v23
	v_or_b32_e32 v58, 58, v23
	v_or_b32_e32 v59, 60, v23
	v_or_b32_e32 v60, 62, v23
	v_lshl_add_u64 v[4:5], s[16:17], 0, v[2:3]
	v_or_b32_e32 v63, 8, v61
	v_or_b32_e32 v64, 16, v61
	v_or_b32_e32 v65, 24, v61
	v_lshl_add_u64 v[6:7], s[18:19], 0, v[2:3]
	v_lshl_add_u64 v[10:11], s[20:21], 0, v[2:3]
	v_lshl_add_u64 v[14:15], s[30:31], 0, v[2:3]
	v_lshl_add_u64 v[18:19], s[6:7], 0, v[2:3]
	s_lshl_b32 s47, s1, 8
	s_lshl_b32 s48, s42, 4
	s_lshl_b32 s49, s1, 7
	s_lshl_b32 s65, s1, 5
	v_or_b32_e32 v69, v69, v22
	s_lshl_b32 s75, s1, 14
	s_add_i32 s76, s0, 0xffffb500
	s_lshl_b32 s77, s1, 4
	s_add_i32 s78, s46, 0xfffc9000
	s_add_i32 s79, s46, 0xfffd4000
	s_movk_i32 s73, 0x4000
	s_mov_b32 s88, 0x10000
	s_mov_b32 s89, 0x16000
	s_mov_b32 s90, 0x2a000
	s_mov_b32 s94, 0x2e000
	s_movk_i32 s95, 0x7fff
	s_mov_b32 s96, 0xffff0000
	s_mov_b32 s97, 0x84000
	s_mov_b32 s22, 0x89000
	s_mov_b32 s23, 0x8f000
	v_add_u32_e32 v70, v24, v20
	v_add_u32_e32 v71, v24, v21
	v_add_u32_e32 v72, v24, v72
	v_add_u32_e32 v73, v24, v73
	v_add_u32_e32 v74, v24, v74
	v_add_u32_e32 v75, v24, v75
	v_add_u32_e32 v76, v24, v76
	v_add_u32_e32 v77, v24, v77
	v_add_u32_e32 v78, v24, v78
	v_add_u32_e32 v79, v24, v79
	v_add_u32_e32 v80, v24, v80
	v_add_u32_e32 v81, v24, v82
	v_add_u32_e32 v82, v24, v83
	v_add_u32_e32 v83, v24, v84
	v_add_u32_e32 v84, v24, v85
	s_mov_b32 s45, 0x26000
	s_mov_b32 s68, 0x38000
	s_mov_b32 s14, 0x3c000
	v_mov_b32_e32 v85, 0x43
	v_mov_b32_e32 v86, 0x45
	v_mov_b32_e32 v87, 0x47
	v_mov_b32_e32 v88, 0x49
	v_mov_b32_e32 v89, 0x4b
	v_mov_b32_e32 v90, 0x4d
	v_mov_b32_e32 v91, 0x4f
	v_mov_b32_e32 v92, 0x51
	v_mov_b32_e32 v93, 0x53
	v_mov_b32_e32 v94, 0x55
	v_mov_b32_e32 v95, 0x57
	v_mov_b32_e32 v96, 0x59
	v_mov_b32_e32 v97, 0x5b
	v_mov_b32_e32 v98, 0x5d
	v_mov_b32_e32 v99, 0x5f
	v_mov_b32_e32 v100, 0x61
	v_mov_b32_e32 v101, 0x63
	v_mov_b32_e32 v102, 0x65
	v_mov_b32_e32 v103, 0x67
	v_mov_b32_e32 v104, 0x69
	v_mov_b32_e32 v105, 0x6b
	v_mov_b32_e32 v106, 0x6d
	v_mov_b32_e32 v107, 0x6f
	v_mov_b32_e32 v108, 0x71
	v_mov_b32_e32 v109, 0x73
	v_mov_b32_e32 v110, 0x75
	v_mov_b32_e32 v111, 0x77
	v_mov_b32_e32 v112, 0x79
	v_mov_b32_e32 v113, 0x7b
	v_mov_b32_e32 v114, 0x7d
	v_mov_b32_e32 v115, 0x7f
	v_mov_b32_e32 v116, 0xff
	s_mov_b32 s15, 0x2c000
	s_mov_b32 s10, 0x30000
	s_mov_b32 s11, 0x32000
	s_mov_b32 s44, 0x34000
	s_mov_b32 s28, 0x36000
	s_mov_b32 s70, 0x3a000
	s_movk_i32 s71, 0x2c00
	s_mov_b32 s35, 0
	s_branch .LBB0_58
.LBB0_57:
	s_add_i32 s42, s42, s43
	s_add_i32 s46, s46, s47
	s_add_i32 s48, s48, s49
	s_add_i32 s64, s64, s65
	s_add_i32 s74, s74, s75
	s_add_i32 s76, s76, s77
	s_add_i32 s78, s78, s47
	s_add_i32 s79, s79, s47
	s_cmp_gt_i32 s42, s99
	s_cbranch_scc1 .LBB0_370

.LBB0_443:
	v_readlane_b32 s0, v254, 8
	v_readlane_b32 s1, v254, 9
	v_readlane_b32 s2, v254, 20
	v_mbcnt_lo_u32_b32 v0, -1, 0
	v_mbcnt_hi_u32_b32 v0, -1, v0
	s_and_b32 s3, s2, 7
	s_lshr_b32 s4, s2, 3
	s_lshl_b32 s5, s4, 3
	s_add_i32 s5, s5, s69
	v_lshlrev_b32_e32 v1, 5, v0
	v_lshlrev_b32_e32 v4, 6, v0
	v_and_b32_e32 v9, 1, v0
	v_lshrrev_b32_e32 v10, 1, v0
	v_mul_u32_u24_e32 v13, 0x900, v9
	v_mul_u32_u24_e32 v14, 0x1600, v9
	v_lshl_add_u32 v13, v10, 8, v13
	v_lshl_add_u32 v14, v10, 8, v14
	s_mul_i32 s8, s3, 0x12000
	s_add_u32 s10, s0, s8
	s_addc_u32 s11, s1, 0
	s_add_u32 s10, s10, 0x100000
	s_addc_u32 s11, s11, 0
	s_add_u32 s22, s10, 12288
	s_addc_u32 s23, s11, 0
	global_load_dwordx4 v[100:103], v4, s[22:23]
	global_load_dwordx4 v[104:107], v4, s[22:23] offset:16
	global_load_dwordx4 v[108:111], v4, s[22:23] offset:32
	global_load_dwordx4 v[112:115], v4, s[22:23] offset:48
	s_add_u32 s22, s22, 0x9000
	s_addc_u32 s23, s23, 0
	global_load_dwordx4 v[116:119], v4, s[22:23]
	global_load_dwordx4 v[120:123], v4, s[22:23] offset:16
	global_load_dwordx4 v[124:127], v4, s[22:23] offset:32
	global_load_dwordx4 v[128:131], v4, s[22:23] offset:48
	s_add_u32 s22, s10, 24576
	s_addc_u32 s23, s11, 0
	global_load_dwordx4 v[16:19], v4, s[22:23]
	global_load_dwordx4 v[20:23], v4, s[22:23] offset:16
	global_load_dwordx4 v[24:27], v4, s[22:23] offset:32
	global_load_dwordx4 v[28:31], v4, s[22:23] offset:48
	s_add_u32 s22, s22, 0x9000
	s_addc_u32 s23, s23, 0
	global_load_dwordx4 v[32:35], v4, s[22:23]
	global_load_dwordx4 v[36:39], v4, s[22:23] offset:16
	global_load_dwordx4 v[40:43], v4, s[22:23] offset:32
	global_load_dwordx4 v[44:47], v4, s[22:23] offset:48
	s_lshl_b32 s8, s5, 11
	s_add_u32 s28, s0, s8
	s_addc_u32 s29, s1, 0
	s_add_u32 s28, s28, 0x3200000
	s_addc_u32 s29, s29, 0
	global_load_dwordx4 v[132:135], v1, s[28:29]
	global_load_dwordx4 v[136:139], v1, s[28:29] offset:16
	s_add_u32 s28, s28, 0x80000
	s_addc_u32 s29, s29, 0
	global_load_dwordx4 v[140:143], v1, s[28:29]
	global_load_dwordx4 v[144:147], v1, s[28:29] offset:16
	s_add_u32 s28, s28, 0x80000
	s_addc_u32 s29, s29, 0
	global_load_dwordx4 v[148:151], v1, s[28:29]
	global_load_dwordx4 v[152:155], v1, s[28:29] offset:16
	s_add_u32 s28, s28, 0x80000
	s_addc_u32 s29, s29, 0
	global_load_dwordx4 v[156:159], v1, s[28:29]
	global_load_dwordx4 v[160:163], v1, s[28:29] offset:16
	s_add_u32 s28, s28, 0x80000
	s_addc_u32 s29, s29, 0
	global_load_dwordx4 v[164:167], v1, s[28:29]
	global_load_dwordx4 v[168:171], v1, s[28:29] offset:16
	s_add_u32 s28, s28, 0x80000
	s_addc_u32 s29, s29, 0
	global_load_dwordx4 v[172:175], v1, s[28:29]
	global_load_dwordx4 v[176:179], v1, s[28:29] offset:16
	s_add_u32 s28, s28, 0x80000
	s_addc_u32 s29, s29, 0
	global_load_dwordx4 v[180:183], v1, s[28:29]
	global_load_dwordx4 v[184:187], v1, s[28:29] offset:16
	s_add_u32 s28, s28, 0x80000
	s_addc_u32 s29, s29, 0
	global_load_dwordx4 v[188:191], v1, s[28:29]
	global_load_dwordx4 v[192:195], v1, s[28:29] offset:16
	s_add_u32 s28, s28, 0x80000
	s_addc_u32 s29, s29, 0
	global_load_dwordx4 v[196:199], v1, s[28:29]
	global_load_dwordx4 v[200:203], v1, s[28:29] offset:16
	s_add_u32 s28, s28, 0x80000
	s_addc_u32 s29, s29, 0
	s_waitcnt vmcnt(0)
	v_lshlrev_b32_e32 v5, 16, v132
	v_and_b32_e32 v6, 0xffff0000, v132
	v_mul_f32_e32 v212, v100, v5
	v_mul_f32_e32 v213, v116, v5
	v_fmac_f32_e32 v212, v101, v6
	v_fmac_f32_e32 v213, v117, v6
	v_lshlrev_b32_e32 v7, 16, v140
	v_and_b32_e32 v8, 0xffff0000, v140
	v_mul_f32_e32 v214, v100, v7
	v_mul_f32_e32 v215, v116, v7
	v_fmac_f32_e32 v214, v101, v8
	v_fmac_f32_e32 v215, v117, v8
	v_lshlrev_b32_e32 v5, 16, v148
	v_and_b32_e32 v6, 0xffff0000, v148
	v_mul_f32_e32 v216, v100, v5
	v_mul_f32_e32 v217, v116, v5
	v_fmac_f32_e32 v216, v101, v6
	v_fmac_f32_e32 v217, v117, v6
	v_lshlrev_b32_e32 v7, 16, v156
	v_and_b32_e32 v8, 0xffff0000, v156
	v_mul_f32_e32 v218, v100, v7
	v_mul_f32_e32 v219, v116, v7
	v_fmac_f32_e32 v218, v101, v8
	v_fmac_f32_e32 v219, v117, v8
	v_lshlrev_b32_e32 v5, 16, v164
	v_and_b32_e32 v6, 0xffff0000, v164
	v_mul_f32_e32 v220, v100, v5
	v_mul_f32_e32 v221, v116, v5
	v_fmac_f32_e32 v220, v101, v6
	v_fmac_f32_e32 v221, v117, v6
	v_lshlrev_b32_e32 v7, 16, v172
	v_and_b32_e32 v8, 0xffff0000, v172
	v_mul_f32_e32 v222, v100, v7
	v_mul_f32_e32 v223, v116, v7
	v_fmac_f32_e32 v222, v101, v8
	v_fmac_f32_e32 v223, v117, v8
	v_lshlrev_b32_e32 v5, 16, v180
	v_and_b32_e32 v6, 0xffff0000, v180
	v_mul_f32_e32 v224, v100, v5
	v_mul_f32_e32 v225, v116, v5
	v_fmac_f32_e32 v224, v101, v6
	v_fmac_f32_e32 v225, v117, v6
	v_lshlrev_b32_e32 v7, 16, v188
	v_and_b32_e32 v8, 0xffff0000, v188
	v_mul_f32_e32 v226, v100, v7
	v_mul_f32_e32 v227, v116, v7
	v_fmac_f32_e32 v226, v101, v8
	v_fmac_f32_e32 v227, v117, v8
	v_lshlrev_b32_e32 v5, 16, v196
	v_and_b32_e32 v6, 0xffff0000, v196
	v_mul_f32_e32 v228, v100, v5
	v_mul_f32_e32 v229, v116, v5
	v_fmac_f32_e32 v228, v101, v6
	v_fmac_f32_e32 v229, v117, v6
	v_lshlrev_b32_e32 v5, 16, v133
	v_and_b32_e32 v6, 0xffff0000, v133
	v_fmac_f32_e32 v212, v102, v5
	v_fmac_f32_e32 v213, v118, v5
	v_fmac_f32_e32 v212, v103, v6
	v_fmac_f32_e32 v213, v119, v6
	v_lshlrev_b32_e32 v7, 16, v141
	v_and_b32_e32 v8, 0xffff0000, v141
	v_fmac_f32_e32 v214, v102, v7
	v_fmac_f32_e32 v215, v118, v7
	v_fmac_f32_e32 v214, v103, v8
	v_fmac_f32_e32 v215, v119, v8
	v_lshlrev_b32_e32 v5, 16, v149
	v_and_b32_e32 v6, 0xffff0000, v149
	v_fmac_f32_e32 v216, v102, v5
	v_fmac_f32_e32 v217, v118, v5
	v_fmac_f32_e32 v216, v103, v6
	v_fmac_f32_e32 v217, v119, v6
	v_lshlrev_b32_e32 v7, 16, v157
	v_and_b32_e32 v8, 0xffff0000, v157
	v_fmac_f32_e32 v218, v102, v7
	v_fmac_f32_e32 v219, v118, v7
	v_fmac_f32_e32 v218, v103, v8
	v_fmac_f32_e32 v219, v119, v8
	v_lshlrev_b32_e32 v5, 16, v165
	v_and_b32_e32 v6, 0xffff0000, v165
	v_fmac_f32_e32 v220, v102, v5
	v_fmac_f32_e32 v221, v118, v5
	v_fmac_f32_e32 v220, v103, v6
	v_fmac_f32_e32 v221, v119, v6
	v_lshlrev_b32_e32 v7, 16, v173
	v_and_b32_e32 v8, 0xffff0000, v173
	v_fmac_f32_e32 v222, v102, v7
	v_fmac_f32_e32 v223, v118, v7
	v_fmac_f32_e32 v222, v103, v8
	v_fmac_f32_e32 v223, v119, v8
	v_lshlrev_b32_e32 v5, 16, v181
	v_and_b32_e32 v6, 0xffff0000, v181
	v_fmac_f32_e32 v224, v102, v5
	v_fmac_f32_e32 v225, v118, v5
	v_fmac_f32_e32 v224, v103, v6
	v_fmac_f32_e32 v225, v119, v6
	v_lshlrev_b32_e32 v7, 16, v189
	v_and_b32_e32 v8, 0xffff0000, v189
	v_fmac_f32_e32 v226, v102, v7
	v_fmac_f32_e32 v227, v118, v7
	v_fmac_f32_e32 v226, v103, v8
	v_fmac_f32_e32 v227, v119, v8
	v_lshlrev_b32_e32 v5, 16, v197
	v_and_b32_e32 v6, 0xffff0000, v197
	v_fmac_f32_e32 v228, v102, v5
	v_fmac_f32_e32 v229, v118, v5
	v_fmac_f32_e32 v228, v103, v6
	v_fmac_f32_e32 v229, v119, v6
	v_lshlrev_b32_e32 v5, 16, v134
	v_and_b32_e32 v6, 0xffff0000, v134
	v_fmac_f32_e32 v212, v104, v5
	v_fmac_f32_e32 v213, v120, v5
	v_fmac_f32_e32 v212, v105, v6
	v_fmac_f32_e32 v213, v121, v6
	v_lshlrev_b32_e32 v7, 16, v142
	v_and_b32_e32 v8, 0xffff0000, v142
	v_fmac_f32_e32 v214, v104, v7
	v_fmac_f32_e32 v215, v120, v7
	v_fmac_f32_e32 v214, v105, v8
	v_fmac_f32_e32 v215, v121, v8
	v_lshlrev_b32_e32 v5, 16, v150
	v_and_b32_e32 v6, 0xffff0000, v150
	v_fmac_f32_e32 v216, v104, v5
	v_fmac_f32_e32 v217, v120, v5
	v_fmac_f32_e32 v216, v105, v6
	v_fmac_f32_e32 v217, v121, v6
	v_lshlrev_b32_e32 v7, 16, v158
	v_and_b32_e32 v8, 0xffff0000, v158
	v_fmac_f32_e32 v218, v104, v7
	v_fmac_f32_e32 v219, v120, v7
	v_fmac_f32_e32 v218, v105, v8
	v_fmac_f32_e32 v219, v121, v8
	v_lshlrev_b32_e32 v5, 16, v166
	v_and_b32_e32 v6, 0xffff0000, v166
	v_fmac_f32_e32 v220, v104, v5
	v_fmac_f32_e32 v221, v120, v5
	v_fmac_f32_e32 v220, v105, v6
	v_fmac_f32_e32 v221, v121, v6
	v_lshlrev_b32_e32 v7, 16, v174
	v_and_b32_e32 v8, 0xffff0000, v174
	v_fmac_f32_e32 v222, v104, v7
	v_fmac_f32_e32 v223, v120, v7
	v_fmac_f32_e32 v222, v105, v8
	v_fmac_f32_e32 v223, v121, v8
	v_lshlrev_b32_e32 v5, 16, v182
	v_and_b32_e32 v6, 0xffff0000, v182
	v_fmac_f32_e32 v224, v104, v5
	v_fmac_f32_e32 v225, v120, v5
	v_fmac_f32_e32 v224, v105, v6
	v_fmac_f32_e32 v225, v121, v6
	v_lshlrev_b32_e32 v7, 16, v190
	v_and_b32_e32 v8, 0xffff0000, v190
	v_fmac_f32_e32 v226, v104, v7
	v_fmac_f32_e32 v227, v120, v7
	v_fmac_f32_e32 v226, v105, v8
	v_fmac_f32_e32 v227, v121, v8
	v_lshlrev_b32_e32 v5, 16, v198
	v_and_b32_e32 v6, 0xffff0000, v198
	v_fmac_f32_e32 v228, v104, v5
	v_fmac_f32_e32 v229, v120, v5
	v_fmac_f32_e32 v228, v105, v6
	v_fmac_f32_e32 v229, v121, v6
	v_lshlrev_b32_e32 v5, 16, v135
	v_and_b32_e32 v6, 0xffff0000, v135
	v_fmac_f32_e32 v212, v106, v5
	v_fmac_f32_e32 v213, v122, v5
	v_fmac_f32_e32 v212, v107, v6
	v_fmac_f32_e32 v213, v123, v6
	v_lshlrev_b32_e32 v7, 16, v143
	v_and_b32_e32 v8, 0xffff0000, v143
	v_fmac_f32_e32 v214, v106, v7
	v_fmac_f32_e32 v215, v122, v7
	v_fmac_f32_e32 v214, v107, v8
	v_fmac_f32_e32 v215, v123, v8
	v_lshlrev_b32_e32 v5, 16, v151
	v_and_b32_e32 v6, 0xffff0000, v151
	v_fmac_f32_e32 v216, v106, v5
	v_fmac_f32_e32 v217, v122, v5
	v_fmac_f32_e32 v216, v107, v6
	v_fmac_f32_e32 v217, v123, v6
	v_lshlrev_b32_e32 v7, 16, v159
	v_and_b32_e32 v8, 0xffff0000, v159
	v_fmac_f32_e32 v218, v106, v7
	v_fmac_f32_e32 v219, v122, v7
	v_fmac_f32_e32 v218, v107, v8
	v_fmac_f32_e32 v219, v123, v8
	v_lshlrev_b32_e32 v5, 16, v167
	v_and_b32_e32 v6, 0xffff0000, v167
	v_fmac_f32_e32 v220, v106, v5
	v_fmac_f32_e32 v221, v122, v5
	v_fmac_f32_e32 v220, v107, v6
	v_fmac_f32_e32 v221, v123, v6
	v_lshlrev_b32_e32 v7, 16, v175
	v_and_b32_e32 v8, 0xffff0000, v175
	v_fmac_f32_e32 v222, v106, v7
	v_fmac_f32_e32 v223, v122, v7
	v_fmac_f32_e32 v222, v107, v8
	v_fmac_f32_e32 v223, v123, v8
	v_lshlrev_b32_e32 v5, 16, v183
	v_and_b32_e32 v6, 0xffff0000, v183
	v_fmac_f32_e32 v224, v106, v5
	v_fmac_f32_e32 v225, v122, v5
	v_fmac_f32_e32 v224, v107, v6
	v_fmac_f32_e32 v225, v123, v6
	v_lshlrev_b32_e32 v7, 16, v191
	v_and_b32_e32 v8, 0xffff0000, v191
	v_fmac_f32_e32 v226, v106, v7
	v_fmac_f32_e32 v227, v122, v7
	v_fmac_f32_e32 v226, v107, v8
	v_fmac_f32_e32 v227, v123, v8
	v_lshlrev_b32_e32 v5, 16, v199
	v_and_b32_e32 v6, 0xffff0000, v199
	v_fmac_f32_e32 v228, v106, v5
	v_fmac_f32_e32 v229, v122, v5
	v_fmac_f32_e32 v228, v107, v6
	v_fmac_f32_e32 v229, v123, v6
	v_lshlrev_b32_e32 v5, 16, v136
	v_and_b32_e32 v6, 0xffff0000, v136
	v_fmac_f32_e32 v212, v108, v5
	v_fmac_f32_e32 v213, v124, v5
	v_fmac_f32_e32 v212, v109, v6
	v_fmac_f32_e32 v213, v125, v6
	v_lshlrev_b32_e32 v7, 16, v144
	v_and_b32_e32 v8, 0xffff0000, v144
	v_fmac_f32_e32 v214, v108, v7
	v_fmac_f32_e32 v215, v124, v7
	v_fmac_f32_e32 v214, v109, v8
	v_fmac_f32_e32 v215, v125, v8
	v_lshlrev_b32_e32 v5, 16, v152
	v_and_b32_e32 v6, 0xffff0000, v152
	v_fmac_f32_e32 v216, v108, v5
	v_fmac_f32_e32 v217, v124, v5
	v_fmac_f32_e32 v216, v109, v6
	v_fmac_f32_e32 v217, v125, v6
	v_lshlrev_b32_e32 v7, 16, v160
	v_and_b32_e32 v8, 0xffff0000, v160
	v_fmac_f32_e32 v218, v108, v7
	v_fmac_f32_e32 v219, v124, v7
	v_fmac_f32_e32 v218, v109, v8
	v_fmac_f32_e32 v219, v125, v8
	v_lshlrev_b32_e32 v5, 16, v168
	v_and_b32_e32 v6, 0xffff0000, v168
	v_fmac_f32_e32 v220, v108, v5
	v_fmac_f32_e32 v221, v124, v5
	v_fmac_f32_e32 v220, v109, v6
	v_fmac_f32_e32 v221, v125, v6
	v_lshlrev_b32_e32 v7, 16, v176
	v_and_b32_e32 v8, 0xffff0000, v176
	v_fmac_f32_e32 v222, v108, v7
	v_fmac_f32_e32 v223, v124, v7
	v_fmac_f32_e32 v222, v109, v8
	v_fmac_f32_e32 v223, v125, v8
	v_lshlrev_b32_e32 v5, 16, v184
	v_and_b32_e32 v6, 0xffff0000, v184
	v_fmac_f32_e32 v224, v108, v5
	v_fmac_f32_e32 v225, v124, v5
	v_fmac_f32_e32 v224, v109, v6
	v_fmac_f32_e32 v225, v125, v6
	v_lshlrev_b32_e32 v7, 16, v192
	v_and_b32_e32 v8, 0xffff0000, v192
	v_fmac_f32_e32 v226, v108, v7
	v_fmac_f32_e32 v227, v124, v7
	v_fmac_f32_e32 v226, v109, v8
	v_fmac_f32_e32 v227, v125, v8
	v_lshlrev_b32_e32 v5, 16, v200
	v_and_b32_e32 v6, 0xffff0000, v200
	v_fmac_f32_e32 v228, v108, v5
	v_fmac_f32_e32 v229, v124, v5
	v_fmac_f32_e32 v228, v109, v6
	v_fmac_f32_e32 v229, v125, v6
	v_lshlrev_b32_e32 v5, 16, v137
	v_and_b32_e32 v6, 0xffff0000, v137
	v_fmac_f32_e32 v212, v110, v5
	v_fmac_f32_e32 v213, v126, v5
	v_fmac_f32_e32 v212, v111, v6
	v_fmac_f32_e32 v213, v127, v6
	v_lshlrev_b32_e32 v7, 16, v145
	v_and_b32_e32 v8, 0xffff0000, v145
	v_fmac_f32_e32 v214, v110, v7
	v_fmac_f32_e32 v215, v126, v7
	v_fmac_f32_e32 v214, v111, v8
	v_fmac_f32_e32 v215, v127, v8
	v_lshlrev_b32_e32 v5, 16, v153
	v_and_b32_e32 v6, 0xffff0000, v153
	v_fmac_f32_e32 v216, v110, v5
	v_fmac_f32_e32 v217, v126, v5
	v_fmac_f32_e32 v216, v111, v6
	v_fmac_f32_e32 v217, v127, v6
	v_lshlrev_b32_e32 v7, 16, v161
	v_and_b32_e32 v8, 0xffff0000, v161
	v_fmac_f32_e32 v218, v110, v7
	v_fmac_f32_e32 v219, v126, v7
	v_fmac_f32_e32 v218, v111, v8
	v_fmac_f32_e32 v219, v127, v8
	v_lshlrev_b32_e32 v5, 16, v169
	v_and_b32_e32 v6, 0xffff0000, v169
	v_fmac_f32_e32 v220, v110, v5
	v_fmac_f32_e32 v221, v126, v5
	v_fmac_f32_e32 v220, v111, v6
	v_fmac_f32_e32 v221, v127, v6
	v_lshlrev_b32_e32 v7, 16, v177
	v_and_b32_e32 v8, 0xffff0000, v177
	v_fmac_f32_e32 v222, v110, v7
	v_fmac_f32_e32 v223, v126, v7
	v_fmac_f32_e32 v222, v111, v8
	v_fmac_f32_e32 v223, v127, v8
	v_lshlrev_b32_e32 v5, 16, v185
	v_and_b32_e32 v6, 0xffff0000, v185
	v_fmac_f32_e32 v224, v110, v5
	v_fmac_f32_e32 v225, v126, v5
	v_fmac_f32_e32 v224, v111, v6
	v_fmac_f32_e32 v225, v127, v6
	v_lshlrev_b32_e32 v7, 16, v193
	v_and_b32_e32 v8, 0xffff0000, v193
	v_fmac_f32_e32 v226, v110, v7
	v_fmac_f32_e32 v227, v126, v7
	v_fmac_f32_e32 v226, v111, v8
	v_fmac_f32_e32 v227, v127, v8
	v_lshlrev_b32_e32 v5, 16, v201
	v_and_b32_e32 v6, 0xffff0000, v201
	v_fmac_f32_e32 v228, v110, v5
	v_fmac_f32_e32 v229, v126, v5
	v_fmac_f32_e32 v228, v111, v6
	v_fmac_f32_e32 v229, v127, v6
	v_lshlrev_b32_e32 v5, 16, v138
	v_and_b32_e32 v6, 0xffff0000, v138
	v_fmac_f32_e32 v212, v112, v5
	v_fmac_f32_e32 v213, v128, v5
	v_fmac_f32_e32 v212, v113, v6
	v_fmac_f32_e32 v213, v129, v6
	v_lshlrev_b32_e32 v7, 16, v146
	v_and_b32_e32 v8, 0xffff0000, v146
	v_fmac_f32_e32 v214, v112, v7
	v_fmac_f32_e32 v215, v128, v7
	v_fmac_f32_e32 v214, v113, v8
	v_fmac_f32_e32 v215, v129, v8
	v_lshlrev_b32_e32 v5, 16, v154
	v_and_b32_e32 v6, 0xffff0000, v154
	v_fmac_f32_e32 v216, v112, v5
	v_fmac_f32_e32 v217, v128, v5
	v_fmac_f32_e32 v216, v113, v6
	v_fmac_f32_e32 v217, v129, v6
	v_lshlrev_b32_e32 v7, 16, v162
	v_and_b32_e32 v8, 0xffff0000, v162
	v_fmac_f32_e32 v218, v112, v7
	v_fmac_f32_e32 v219, v128, v7
	v_fmac_f32_e32 v218, v113, v8
	v_fmac_f32_e32 v219, v129, v8
	v_lshlrev_b32_e32 v5, 16, v170
	v_and_b32_e32 v6, 0xffff0000, v170
	v_fmac_f32_e32 v220, v112, v5
	v_fmac_f32_e32 v221, v128, v5
	v_fmac_f32_e32 v220, v113, v6
	v_fmac_f32_e32 v221, v129, v6
	v_lshlrev_b32_e32 v7, 16, v178
	v_and_b32_e32 v8, 0xffff0000, v178
	v_fmac_f32_e32 v222, v112, v7
	v_fmac_f32_e32 v223, v128, v7
	v_fmac_f32_e32 v222, v113, v8
	v_fmac_f32_e32 v223, v129, v8
	v_lshlrev_b32_e32 v5, 16, v186
	v_and_b32_e32 v6, 0xffff0000, v186
	v_fmac_f32_e32 v224, v112, v5
	v_fmac_f32_e32 v225, v128, v5
	v_fmac_f32_e32 v224, v113, v6
	v_fmac_f32_e32 v225, v129, v6
	v_lshlrev_b32_e32 v7, 16, v194
	v_and_b32_e32 v8, 0xffff0000, v194
	v_fmac_f32_e32 v226, v112, v7
	v_fmac_f32_e32 v227, v128, v7
	v_fmac_f32_e32 v226, v113, v8
	v_fmac_f32_e32 v227, v129, v8
	v_lshlrev_b32_e32 v5, 16, v202
	v_and_b32_e32 v6, 0xffff0000, v202
	v_fmac_f32_e32 v228, v112, v5
	v_fmac_f32_e32 v229, v128, v5
	v_fmac_f32_e32 v228, v113, v6
	v_fmac_f32_e32 v229, v129, v6
	v_lshlrev_b32_e32 v5, 16, v139
	v_and_b32_e32 v6, 0xffff0000, v139
	v_fmac_f32_e32 v212, v114, v5
	v_fmac_f32_e32 v213, v130, v5
	v_fmac_f32_e32 v212, v115, v6
	v_fmac_f32_e32 v213, v131, v6
	v_lshlrev_b32_e32 v7, 16, v147
	v_and_b32_e32 v8, 0xffff0000, v147
	v_fmac_f32_e32 v214, v114, v7
	v_fmac_f32_e32 v215, v130, v7
	v_fmac_f32_e32 v214, v115, v8
	v_fmac_f32_e32 v215, v131, v8
	v_lshlrev_b32_e32 v5, 16, v155
	v_and_b32_e32 v6, 0xffff0000, v155
	v_fmac_f32_e32 v216, v114, v5
	v_fmac_f32_e32 v217, v130, v5
	v_fmac_f32_e32 v216, v115, v6
	v_fmac_f32_e32 v217, v131, v6
	v_lshlrev_b32_e32 v7, 16, v163
	v_and_b32_e32 v8, 0xffff0000, v163
	v_fmac_f32_e32 v218, v114, v7
	v_fmac_f32_e32 v219, v130, v7
	v_fmac_f32_e32 v218, v115, v8
	v_fmac_f32_e32 v219, v131, v8
	v_lshlrev_b32_e32 v5, 16, v171
	v_and_b32_e32 v6, 0xffff0000, v171
	v_fmac_f32_e32 v220, v114, v5
	v_fmac_f32_e32 v221, v130, v5
	v_fmac_f32_e32 v220, v115, v6
	v_fmac_f32_e32 v221, v131, v6
	v_lshlrev_b32_e32 v7, 16, v179
	v_and_b32_e32 v8, 0xffff0000, v179
	v_fmac_f32_e32 v222, v114, v7
	v_fmac_f32_e32 v223, v130, v7
	v_fmac_f32_e32 v222, v115, v8
	v_fmac_f32_e32 v223, v131, v8
	v_lshlrev_b32_e32 v5, 16, v187
	v_and_b32_e32 v6, 0xffff0000, v187
	v_fmac_f32_e32 v224, v114, v5
	v_fmac_f32_e32 v225, v130, v5
	v_fmac_f32_e32 v224, v115, v6
	v_fmac_f32_e32 v225, v131, v6
	v_lshlrev_b32_e32 v7, 16, v195
	v_and_b32_e32 v8, 0xffff0000, v195
	v_fmac_f32_e32 v226, v114, v7
	v_fmac_f32_e32 v227, v130, v7
	v_fmac_f32_e32 v226, v115, v8
	v_fmac_f32_e32 v227, v131, v8
	v_lshlrev_b32_e32 v5, 16, v203
	v_and_b32_e32 v6, 0xffff0000, v203
	v_fmac_f32_e32 v228, v114, v5
	v_fmac_f32_e32 v229, v130, v5
	v_fmac_f32_e32 v228, v115, v6
	v_fmac_f32_e32 v229, v131, v6
	s_lshl_b32 s8, s5, 11
	s_add_u32 s28, s0, s8
	s_addc_u32 s29, s1, 0
	s_add_u32 s28, s28, 0x2100000
	s_addc_u32 s29, s29, 0
	global_load_dwordx4 v[132:135], v1, s[28:29]
	global_load_dwordx4 v[136:139], v1, s[28:29] offset:16
	s_add_u32 s28, s28, 0x80000
	s_addc_u32 s29, s29, 0
	global_load_dwordx4 v[140:143], v1, s[28:29]
	global_load_dwordx4 v[144:147], v1, s[28:29] offset:16
	s_add_u32 s28, s28, 0x80000
	s_addc_u32 s29, s29, 0
	global_load_dwordx4 v[148:151], v1, s[28:29]
	global_load_dwordx4 v[152:155], v1, s[28:29] offset:16
	s_add_u32 s28, s28, 0x80000
	s_addc_u32 s29, s29, 0
	global_load_dwordx4 v[156:159], v1, s[28:29]
	global_load_dwordx4 v[160:163], v1, s[28:29] offset:16
	s_add_u32 s28, s28, 0x80000
	s_addc_u32 s29, s29, 0
	global_load_dwordx4 v[164:167], v1, s[28:29]
	global_load_dwordx4 v[168:171], v1, s[28:29] offset:16
	s_add_u32 s28, s28, 0x80000
	s_addc_u32 s29, s29, 0
	global_load_dwordx4 v[172:175], v1, s[28:29]
	global_load_dwordx4 v[176:179], v1, s[28:29] offset:16
	s_add_u32 s28, s28, 0x80000
	s_addc_u32 s29, s29, 0
	global_load_dwordx4 v[180:183], v1, s[28:29]
	global_load_dwordx4 v[184:187], v1, s[28:29] offset:16
	s_add_u32 s28, s28, 0x80000
	s_addc_u32 s29, s29, 0
	global_load_dwordx4 v[188:191], v1, s[28:29]
	global_load_dwordx4 v[192:195], v1, s[28:29] offset:16
	s_add_u32 s28, s28, 0x80000
	s_addc_u32 s29, s29, 0
	global_load_dwordx4 v[196:199], v1, s[28:29]
	global_load_dwordx4 v[200:203], v1, s[28:29] offset:16
	s_add_u32 s28, s28, 0x80000
	s_addc_u32 s29, s29, 0
	v_add_f32_dpp v212, v212, v212 quad_perm:[1,0,3,2] row_mask:0xf bank_mask:0xf
	v_add_f32_dpp v213, v213, v213 quad_perm:[1,0,3,2] row_mask:0xf bank_mask:0xf
	v_add_f32_dpp v214, v214, v214 quad_perm:[1,0,3,2] row_mask:0xf bank_mask:0xf
	v_add_f32_dpp v215, v215, v215 quad_perm:[1,0,3,2] row_mask:0xf bank_mask:0xf
	v_add_f32_dpp v216, v216, v216 quad_perm:[1,0,3,2] row_mask:0xf bank_mask:0xf
	v_add_f32_dpp v217, v217, v217 quad_perm:[1,0,3,2] row_mask:0xf bank_mask:0xf
	v_add_f32_dpp v218, v218, v218 quad_perm:[1,0,3,2] row_mask:0xf bank_mask:0xf
	v_add_f32_dpp v219, v219, v219 quad_perm:[1,0,3,2] row_mask:0xf bank_mask:0xf
	v_add_f32_dpp v220, v220, v220 quad_perm:[1,0,3,2] row_mask:0xf bank_mask:0xf
	v_add_f32_dpp v221, v221, v221 quad_perm:[1,0,3,2] row_mask:0xf bank_mask:0xf
	v_add_f32_dpp v222, v222, v222 quad_perm:[1,0,3,2] row_mask:0xf bank_mask:0xf
	v_add_f32_dpp v223, v223, v223 quad_perm:[1,0,3,2] row_mask:0xf bank_mask:0xf
	v_add_f32_dpp v224, v224, v224 quad_perm:[1,0,3,2] row_mask:0xf bank_mask:0xf
	v_add_f32_dpp v225, v225, v225 quad_perm:[1,0,3,2] row_mask:0xf bank_mask:0xf
	v_add_f32_dpp v226, v226, v226 quad_perm:[1,0,3,2] row_mask:0xf bank_mask:0xf
	v_add_f32_dpp v227, v227, v227 quad_perm:[1,0,3,2] row_mask:0xf bank_mask:0xf
	v_add_f32_dpp v228, v228, v228 quad_perm:[1,0,3,2] row_mask:0xf bank_mask:0xf
	v_add_f32_dpp v229, v229, v229 quad_perm:[1,0,3,2] row_mask:0xf bank_mask:0xf
	v_add_f32_dpp v212, v212, v212 quad_perm:[2,3,0,1] row_mask:0xf bank_mask:0xf
	v_add_f32_dpp v213, v213, v213 quad_perm:[2,3,0,1] row_mask:0xf bank_mask:0xf
	v_add_f32_dpp v214, v214, v214 quad_perm:[2,3,0,1] row_mask:0xf bank_mask:0xf
	v_add_f32_dpp v215, v215, v215 quad_perm:[2,3,0,1] row_mask:0xf bank_mask:0xf
	v_add_f32_dpp v216, v216, v216 quad_perm:[2,3,0,1] row_mask:0xf bank_mask:0xf
	v_add_f32_dpp v217, v217, v217 quad_perm:[2,3,0,1] row_mask:0xf bank_mask:0xf
	v_add_f32_dpp v218, v218, v218 quad_perm:[2,3,0,1] row_mask:0xf bank_mask:0xf
	v_add_f32_dpp v219, v219, v219 quad_perm:[2,3,0,1] row_mask:0xf bank_mask:0xf
	v_add_f32_dpp v220, v220, v220 quad_perm:[2,3,0,1] row_mask:0xf bank_mask:0xf
	v_add_f32_dpp v221, v221, v221 quad_perm:[2,3,0,1] row_mask:0xf bank_mask:0xf
	v_add_f32_dpp v222, v222, v222 quad_perm:[2,3,0,1] row_mask:0xf bank_mask:0xf
	v_add_f32_dpp v223, v223, v223 quad_perm:[2,3,0,1] row_mask:0xf bank_mask:0xf
	v_add_f32_dpp v224, v224, v224 quad_perm:[2,3,0,1] row_mask:0xf bank_mask:0xf
	v_add_f32_dpp v225, v225, v225 quad_perm:[2,3,0,1] row_mask:0xf bank_mask:0xf
	v_add_f32_dpp v226, v226, v226 quad_perm:[2,3,0,1] row_mask:0xf bank_mask:0xf
	v_add_f32_dpp v227, v227, v227 quad_perm:[2,3,0,1] row_mask:0xf bank_mask:0xf
	v_add_f32_dpp v228, v228, v228 quad_perm:[2,3,0,1] row_mask:0xf bank_mask:0xf
	v_add_f32_dpp v229, v229, v229 quad_perm:[2,3,0,1] row_mask:0xf bank_mask:0xf
	v_add_f32_dpp v212, v212, v212 row_half_mirror row_mask:0xf bank_mask:0xf
	v_add_f32_dpp v213, v213, v213 row_half_mirror row_mask:0xf bank_mask:0xf
	v_add_f32_dpp v214, v214, v214 row_half_mirror row_mask:0xf bank_mask:0xf
	v_add_f32_dpp v215, v215, v215 row_half_mirror row_mask:0xf bank_mask:0xf
	v_add_f32_dpp v216, v216, v216 row_half_mirror row_mask:0xf bank_mask:0xf
	v_add_f32_dpp v217, v217, v217 row_half_mirror row_mask:0xf bank_mask:0xf
	v_add_f32_dpp v218, v218, v218 row_half_mirror row_mask:0xf bank_mask:0xf
	v_add_f32_dpp v219, v219, v219 row_half_mirror row_mask:0xf bank_mask:0xf
	v_add_f32_dpp v220, v220, v220 row_half_mirror row_mask:0xf bank_mask:0xf
	v_add_f32_dpp v221, v221, v221 row_half_mirror row_mask:0xf bank_mask:0xf
	v_add_f32_dpp v222, v222, v222 row_half_mirror row_mask:0xf bank_mask:0xf
	v_add_f32_dpp v223, v223, v223 row_half_mirror row_mask:0xf bank_mask:0xf
	v_add_f32_dpp v224, v224, v224 row_half_mirror row_mask:0xf bank_mask:0xf
	v_add_f32_dpp v225, v225, v225 row_half_mirror row_mask:0xf bank_mask:0xf
	v_add_f32_dpp v226, v226, v226 row_half_mirror row_mask:0xf bank_mask:0xf
	v_add_f32_dpp v227, v227, v227 row_half_mirror row_mask:0xf bank_mask:0xf
	v_add_f32_dpp v228, v228, v228 row_half_mirror row_mask:0xf bank_mask:0xf
	v_add_f32_dpp v229, v229, v229 row_half_mirror row_mask:0xf bank_mask:0xf
	v_add_f32_dpp v212, v212, v212 row_mirror row_mask:0xf bank_mask:0xf
	v_add_f32_dpp v213, v213, v213 row_mirror row_mask:0xf bank_mask:0xf
	v_add_f32_dpp v214, v214, v214 row_mirror row_mask:0xf bank_mask:0xf
	v_add_f32_dpp v215, v215, v215 row_mirror row_mask:0xf bank_mask:0xf
	v_add_f32_dpp v216, v216, v216 row_mirror row_mask:0xf bank_mask:0xf
	v_add_f32_dpp v217, v217, v217 row_mirror row_mask:0xf bank_mask:0xf
	v_add_f32_dpp v218, v218, v218 row_mirror row_mask:0xf bank_mask:0xf
	v_add_f32_dpp v219, v219, v219 row_mirror row_mask:0xf bank_mask:0xf
	v_add_f32_dpp v220, v220, v220 row_mirror row_mask:0xf bank_mask:0xf
	v_add_f32_dpp v221, v221, v221 row_mirror row_mask:0xf bank_mask:0xf
	v_add_f32_dpp v222, v222, v222 row_mirror row_mask:0xf bank_mask:0xf
	v_add_f32_dpp v223, v223, v223 row_mirror row_mask:0xf bank_mask:0xf
	v_add_f32_dpp v224, v224, v224 row_mirror row_mask:0xf bank_mask:0xf
	v_add_f32_dpp v225, v225, v225 row_mirror row_mask:0xf bank_mask:0xf
	v_add_f32_dpp v226, v226, v226 row_mirror row_mask:0xf bank_mask:0xf
	v_add_f32_dpp v227, v227, v227 row_mirror row_mask:0xf bank_mask:0xf
	v_add_f32_dpp v228, v228, v228 row_mirror row_mask:0xf bank_mask:0xf
	v_add_f32_dpp v229, v229, v229 row_mirror row_mask:0xf bank_mask:0xf
	v_add_f32_dpp v212, v212, v212 row_bcast:15 row_mask:0xa bank_mask:0xf
	v_add_f32_dpp v213, v213, v213 row_bcast:15 row_mask:0xa bank_mask:0xf
	v_add_f32_dpp v214, v214, v214 row_bcast:15 row_mask:0xa bank_mask:0xf
	v_add_f32_dpp v215, v215, v215 row_bcast:15 row_mask:0xa bank_mask:0xf
	v_add_f32_dpp v216, v216, v216 row_bcast:15 row_mask:0xa bank_mask:0xf
	v_add_f32_dpp v217, v217, v217 row_bcast:15 row_mask:0xa bank_mask:0xf
	v_add_f32_dpp v218, v218, v218 row_bcast:15 row_mask:0xa bank_mask:0xf
	v_add_f32_dpp v219, v219, v219 row_bcast:15 row_mask:0xa bank_mask:0xf
	v_add_f32_dpp v220, v220, v220 row_bcast:15 row_mask:0xa bank_mask:0xf
	v_add_f32_dpp v221, v221, v221 row_bcast:15 row_mask:0xa bank_mask:0xf
	v_add_f32_dpp v222, v222, v222 row_bcast:15 row_mask:0xa bank_mask:0xf
	v_add_f32_dpp v223, v223, v223 row_bcast:15 row_mask:0xa bank_mask:0xf
	v_add_f32_dpp v224, v224, v224 row_bcast:15 row_mask:0xa bank_mask:0xf
	v_add_f32_dpp v225, v225, v225 row_bcast:15 row_mask:0xa bank_mask:0xf
	v_add_f32_dpp v226, v226, v226 row_bcast:15 row_mask:0xa bank_mask:0xf
	v_add_f32_dpp v227, v227, v227 row_bcast:15 row_mask:0xa bank_mask:0xf
	v_add_f32_dpp v228, v228, v228 row_bcast:15 row_mask:0xa bank_mask:0xf
	v_add_f32_dpp v229, v229, v229 row_bcast:15 row_mask:0xa bank_mask:0xf
	v_add_f32_dpp v212, v212, v212 row_bcast:31 row_mask:0xc bank_mask:0xf
	v_add_f32_dpp v213, v213, v213 row_bcast:31 row_mask:0xc bank_mask:0xf
	v_add_f32_dpp v214, v214, v214 row_bcast:31 row_mask:0xc bank_mask:0xf
	v_add_f32_dpp v215, v215, v215 row_bcast:31 row_mask:0xc bank_mask:0xf
	v_add_f32_dpp v216, v216, v216 row_bcast:31 row_mask:0xc bank_mask:0xf
	v_add_f32_dpp v217, v217, v217 row_bcast:31 row_mask:0xc bank_mask:0xf
	v_add_f32_dpp v218, v218, v218 row_bcast:31 row_mask:0xc bank_mask:0xf
	v_add_f32_dpp v219, v219, v219 row_bcast:31 row_mask:0xc bank_mask:0xf
	v_add_f32_dpp v220, v220, v220 row_bcast:31 row_mask:0xc bank_mask:0xf
	v_add_f32_dpp v221, v221, v221 row_bcast:31 row_mask:0xc bank_mask:0xf
	v_add_f32_dpp v222, v222, v222 row_bcast:31 row_mask:0xc bank_mask:0xf
	v_add_f32_dpp v223, v223, v223 row_bcast:31 row_mask:0xc bank_mask:0xf
	v_add_f32_dpp v224, v224, v224 row_bcast:31 row_mask:0xc bank_mask:0xf
	v_add_f32_dpp v225, v225, v225 row_bcast:31 row_mask:0xc bank_mask:0xf
	v_add_f32_dpp v226, v226, v226 row_bcast:31 row_mask:0xc bank_mask:0xf
	v_add_f32_dpp v227, v227, v227 row_bcast:31 row_mask:0xc bank_mask:0xf
	v_add_f32_dpp v228, v228, v228 row_bcast:31 row_mask:0xc bank_mask:0xf
	v_add_f32_dpp v229, v229, v229 row_bcast:31 row_mask:0xc bank_mask:0xf
	s_nop 0
	v_readlane_b32 s32, v212, 63
	v_readlane_b32 s33, v213, 63
	v_readlane_b32 s40, v214, 63
	v_readlane_b32 s41, v215, 63
	v_readlane_b32 s46, v216, 63
	v_readlane_b32 s47, v217, 63
	v_readlane_b32 s51, v218, 63
	v_readlane_b32 s57, v219, 63
	v_readlane_b32 s58, v220, 63
	v_readlane_b32 s59, v221, 63
	v_readlane_b32 s60, v222, 63
	v_readlane_b32 s61, v223, 63
	v_readlane_b32 s62, v224, 63
	v_readlane_b32 s63, v225, 63
	v_readlane_b32 s70, v226, 63
	v_readlane_b32 s71, v227, 63
	v_readlane_b32 s74, v228, 63
	v_readlane_b32 s75, v229, 63
	s_nop 1
	v_writelane_b32 v9, s32, 0
	v_writelane_b32 v9, s33, 1
	v_writelane_b32 v9, s40, 2
	v_writelane_b32 v9, s41, 3
	v_writelane_b32 v9, s46, 4
	v_writelane_b32 v9, s47, 5
	v_writelane_b32 v9, s51, 6
	v_writelane_b32 v9, s57, 7
	v_writelane_b32 v9, s58, 8
	v_writelane_b32 v9, s59, 9
	v_writelane_b32 v9, s60, 10
	v_writelane_b32 v9, s61, 11
	v_writelane_b32 v9, s62, 12
	v_writelane_b32 v9, s63, 13
	v_writelane_b32 v9, s70, 14
	v_writelane_b32 v9, s71, 15
	v_writelane_b32 v9, s74, 16
	v_writelane_b32 v9, s75, 17
	s_mul_i32 s91, s3, 4608
	s_add_i32 s91, s91, s5
	s_add_u32 s8, s0, 0x3d00000
	s_addc_u32 s9, s1, 0
	v_add_u32_e32 v15, s91, v13
	v_lshlrev_b32_e32 v15, 2, v15
	s_mov_b64 exec, 0x3ffff
	global_store_dword v15, v9, s[8:9]
	s_mov_b64 exec, -1
	s_waitcnt vmcnt(0)
	v_lshlrev_b32_e32 v5, 16, v132
	v_and_b32_e32 v6, 0xffff0000, v132
	v_mul_f32_e32 v212, v16, v5
	v_mul_f32_e32 v213, v32, v5
	v_fmac_f32_e32 v212, v17, v6
	v_fmac_f32_e32 v213, v33, v6
	v_lshlrev_b32_e32 v7, 16, v140
	v_and_b32_e32 v8, 0xffff0000, v140
	v_mul_f32_e32 v214, v16, v7
	v_mul_f32_e32 v215, v32, v7
	v_fmac_f32_e32 v214, v17, v8
	v_fmac_f32_e32 v215, v33, v8
	v_lshlrev_b32_e32 v5, 16, v148
	v_and_b32_e32 v6, 0xffff0000, v148
	v_mul_f32_e32 v216, v16, v5
	v_mul_f32_e32 v217, v32, v5
	v_fmac_f32_e32 v216, v17, v6
	v_fmac_f32_e32 v217, v33, v6
	v_lshlrev_b32_e32 v7, 16, v156
	v_and_b32_e32 v8, 0xffff0000, v156
	v_mul_f32_e32 v218, v16, v7
	v_mul_f32_e32 v219, v32, v7
	v_fmac_f32_e32 v218, v17, v8
	v_fmac_f32_e32 v219, v33, v8
	v_lshlrev_b32_e32 v5, 16, v164
	v_and_b32_e32 v6, 0xffff0000, v164
	v_mul_f32_e32 v220, v16, v5
	v_mul_f32_e32 v221, v32, v5
	v_fmac_f32_e32 v220, v17, v6
	v_fmac_f32_e32 v221, v33, v6
	v_lshlrev_b32_e32 v7, 16, v172
	v_and_b32_e32 v8, 0xffff0000, v172
	v_mul_f32_e32 v222, v16, v7
	v_mul_f32_e32 v223, v32, v7
	v_fmac_f32_e32 v222, v17, v8
	v_fmac_f32_e32 v223, v33, v8
	v_lshlrev_b32_e32 v5, 16, v180
	v_and_b32_e32 v6, 0xffff0000, v180
	v_mul_f32_e32 v224, v16, v5
	v_mul_f32_e32 v225, v32, v5
	v_fmac_f32_e32 v224, v17, v6
	v_fmac_f32_e32 v225, v33, v6
	v_lshlrev_b32_e32 v7, 16, v188
	v_and_b32_e32 v8, 0xffff0000, v188
	v_mul_f32_e32 v226, v16, v7
	v_mul_f32_e32 v227, v32, v7
	v_fmac_f32_e32 v226, v17, v8
	v_fmac_f32_e32 v227, v33, v8
	v_lshlrev_b32_e32 v5, 16, v196
	v_and_b32_e32 v6, 0xffff0000, v196
	v_mul_f32_e32 v228, v16, v5
	v_mul_f32_e32 v229, v32, v5
	v_fmac_f32_e32 v228, v17, v6
	v_fmac_f32_e32 v229, v33, v6
	v_lshlrev_b32_e32 v5, 16, v133
	v_and_b32_e32 v6, 0xffff0000, v133
	v_fmac_f32_e32 v212, v18, v5
	v_fmac_f32_e32 v213, v34, v5
	v_fmac_f32_e32 v212, v19, v6
	v_fmac_f32_e32 v213, v35, v6
	v_lshlrev_b32_e32 v7, 16, v141
	v_and_b32_e32 v8, 0xffff0000, v141
	v_fmac_f32_e32 v214, v18, v7
	v_fmac_f32_e32 v215, v34, v7
	v_fmac_f32_e32 v214, v19, v8
	v_fmac_f32_e32 v215, v35, v8
	v_lshlrev_b32_e32 v5, 16, v149
	v_and_b32_e32 v6, 0xffff0000, v149
	v_fmac_f32_e32 v216, v18, v5
	v_fmac_f32_e32 v217, v34, v5
	v_fmac_f32_e32 v216, v19, v6
	v_fmac_f32_e32 v217, v35, v6
	v_lshlrev_b32_e32 v7, 16, v157
	v_and_b32_e32 v8, 0xffff0000, v157
	v_fmac_f32_e32 v218, v18, v7
	v_fmac_f32_e32 v219, v34, v7
	v_fmac_f32_e32 v218, v19, v8
	v_fmac_f32_e32 v219, v35, v8
	v_lshlrev_b32_e32 v5, 16, v165
	v_and_b32_e32 v6, 0xffff0000, v165
	v_fmac_f32_e32 v220, v18, v5
	v_fmac_f32_e32 v221, v34, v5
	v_fmac_f32_e32 v220, v19, v6
	v_fmac_f32_e32 v221, v35, v6
	v_lshlrev_b32_e32 v7, 16, v173
	v_and_b32_e32 v8, 0xffff0000, v173
	v_fmac_f32_e32 v222, v18, v7
	v_fmac_f32_e32 v223, v34, v7
	v_fmac_f32_e32 v222, v19, v8
	v_fmac_f32_e32 v223, v35, v8
	v_lshlrev_b32_e32 v5, 16, v181
	v_and_b32_e32 v6, 0xffff0000, v181
	v_fmac_f32_e32 v224, v18, v5
	v_fmac_f32_e32 v225, v34, v5
	v_fmac_f32_e32 v224, v19, v6
	v_fmac_f32_e32 v225, v35, v6
	v_lshlrev_b32_e32 v7, 16, v189
	v_and_b32_e32 v8, 0xffff0000, v189
	v_fmac_f32_e32 v226, v18, v7
	v_fmac_f32_e32 v227, v34, v7
	v_fmac_f32_e32 v226, v19, v8
	v_fmac_f32_e32 v227, v35, v8
	v_lshlrev_b32_e32 v5, 16, v197
	v_and_b32_e32 v6, 0xffff0000, v197
	v_fmac_f32_e32 v228, v18, v5
	v_fmac_f32_e32 v229, v34, v5
	v_fmac_f32_e32 v228, v19, v6
	v_fmac_f32_e32 v229, v35, v6
	v_lshlrev_b32_e32 v5, 16, v134
	v_and_b32_e32 v6, 0xffff0000, v134
	v_fmac_f32_e32 v212, v20, v5
	v_fmac_f32_e32 v213, v36, v5
	v_fmac_f32_e32 v212, v21, v6
	v_fmac_f32_e32 v213, v37, v6
	v_lshlrev_b32_e32 v7, 16, v142
	v_and_b32_e32 v8, 0xffff0000, v142
	v_fmac_f32_e32 v214, v20, v7
	v_fmac_f32_e32 v215, v36, v7
	v_fmac_f32_e32 v214, v21, v8
	v_fmac_f32_e32 v215, v37, v8
	v_lshlrev_b32_e32 v5, 16, v150
	v_and_b32_e32 v6, 0xffff0000, v150
	v_fmac_f32_e32 v216, v20, v5
	v_fmac_f32_e32 v217, v36, v5
	v_fmac_f32_e32 v216, v21, v6
	v_fmac_f32_e32 v217, v37, v6
	v_lshlrev_b32_e32 v7, 16, v158
	v_and_b32_e32 v8, 0xffff0000, v158
	v_fmac_f32_e32 v218, v20, v7
	v_fmac_f32_e32 v219, v36, v7
	v_fmac_f32_e32 v218, v21, v8
	v_fmac_f32_e32 v219, v37, v8
	v_lshlrev_b32_e32 v5, 16, v166
	v_and_b32_e32 v6, 0xffff0000, v166
	v_fmac_f32_e32 v220, v20, v5
	v_fmac_f32_e32 v221, v36, v5
	v_fmac_f32_e32 v220, v21, v6
	v_fmac_f32_e32 v221, v37, v6
	v_lshlrev_b32_e32 v7, 16, v174
	v_and_b32_e32 v8, 0xffff0000, v174
	v_fmac_f32_e32 v222, v20, v7
	v_fmac_f32_e32 v223, v36, v7
	v_fmac_f32_e32 v222, v21, v8
	v_fmac_f32_e32 v223, v37, v8
	v_lshlrev_b32_e32 v5, 16, v182
	v_and_b32_e32 v6, 0xffff0000, v182
	v_fmac_f32_e32 v224, v20, v5
	v_fmac_f32_e32 v225, v36, v5
	v_fmac_f32_e32 v224, v21, v6
	v_fmac_f32_e32 v225, v37, v6
	v_lshlrev_b32_e32 v7, 16, v190
	v_and_b32_e32 v8, 0xffff0000, v190
	v_fmac_f32_e32 v226, v20, v7
	v_fmac_f32_e32 v227, v36, v7
	v_fmac_f32_e32 v226, v21, v8
	v_fmac_f32_e32 v227, v37, v8
	v_lshlrev_b32_e32 v5, 16, v198
	v_and_b32_e32 v6, 0xffff0000, v198
	v_fmac_f32_e32 v228, v20, v5
	v_fmac_f32_e32 v229, v36, v5
	v_fmac_f32_e32 v228, v21, v6
	v_fmac_f32_e32 v229, v37, v6
	v_lshlrev_b32_e32 v5, 16, v135
	v_and_b32_e32 v6, 0xffff0000, v135
	v_fmac_f32_e32 v212, v22, v5
	v_fmac_f32_e32 v213, v38, v5
	v_fmac_f32_e32 v212, v23, v6
	v_fmac_f32_e32 v213, v39, v6
	v_lshlrev_b32_e32 v7, 16, v143
	v_and_b32_e32 v8, 0xffff0000, v143
	v_fmac_f32_e32 v214, v22, v7
	v_fmac_f32_e32 v215, v38, v7
	v_fmac_f32_e32 v214, v23, v8
	v_fmac_f32_e32 v215, v39, v8
	v_lshlrev_b32_e32 v5, 16, v151
	v_and_b32_e32 v6, 0xffff0000, v151
	v_fmac_f32_e32 v216, v22, v5
	v_fmac_f32_e32 v217, v38, v5
	v_fmac_f32_e32 v216, v23, v6
	v_fmac_f32_e32 v217, v39, v6
	v_lshlrev_b32_e32 v7, 16, v159
	v_and_b32_e32 v8, 0xffff0000, v159
	v_fmac_f32_e32 v218, v22, v7
	v_fmac_f32_e32 v219, v38, v7
	v_fmac_f32_e32 v218, v23, v8
	v_fmac_f32_e32 v219, v39, v8
	v_lshlrev_b32_e32 v5, 16, v167
	v_and_b32_e32 v6, 0xffff0000, v167
	v_fmac_f32_e32 v220, v22, v5
	v_fmac_f32_e32 v221, v38, v5
	v_fmac_f32_e32 v220, v23, v6
	v_fmac_f32_e32 v221, v39, v6
	v_lshlrev_b32_e32 v7, 16, v175
	v_and_b32_e32 v8, 0xffff0000, v175
	v_fmac_f32_e32 v222, v22, v7
	v_fmac_f32_e32 v223, v38, v7
	v_fmac_f32_e32 v222, v23, v8
	v_fmac_f32_e32 v223, v39, v8
	v_lshlrev_b32_e32 v5, 16, v183
	v_and_b32_e32 v6, 0xffff0000, v183
	v_fmac_f32_e32 v224, v22, v5
	v_fmac_f32_e32 v225, v38, v5
	v_fmac_f32_e32 v224, v23, v6
	v_fmac_f32_e32 v225, v39, v6
	v_lshlrev_b32_e32 v7, 16, v191
	v_and_b32_e32 v8, 0xffff0000, v191
	v_fmac_f32_e32 v226, v22, v7
	v_fmac_f32_e32 v227, v38, v7
	v_fmac_f32_e32 v226, v23, v8
	v_fmac_f32_e32 v227, v39, v8
	v_lshlrev_b32_e32 v5, 16, v199
	v_and_b32_e32 v6, 0xffff0000, v199
	v_fmac_f32_e32 v228, v22, v5
	v_fmac_f32_e32 v229, v38, v5
	v_fmac_f32_e32 v228, v23, v6
	v_fmac_f32_e32 v229, v39, v6
	v_lshlrev_b32_e32 v5, 16, v136
	v_and_b32_e32 v6, 0xffff0000, v136
	v_fmac_f32_e32 v212, v24, v5
	v_fmac_f32_e32 v213, v40, v5
	v_fmac_f32_e32 v212, v25, v6
	v_fmac_f32_e32 v213, v41, v6
	v_lshlrev_b32_e32 v7, 16, v144
	v_and_b32_e32 v8, 0xffff0000, v144
	v_fmac_f32_e32 v214, v24, v7
	v_fmac_f32_e32 v215, v40, v7
	v_fmac_f32_e32 v214, v25, v8
	v_fmac_f32_e32 v215, v41, v8
	v_lshlrev_b32_e32 v5, 16, v152
	v_and_b32_e32 v6, 0xffff0000, v152
	v_fmac_f32_e32 v216, v24, v5
	v_fmac_f32_e32 v217, v40, v5
	v_fmac_f32_e32 v216, v25, v6
	v_fmac_f32_e32 v217, v41, v6
	v_lshlrev_b32_e32 v7, 16, v160
	v_and_b32_e32 v8, 0xffff0000, v160
	v_fmac_f32_e32 v218, v24, v7
	v_fmac_f32_e32 v219, v40, v7
	v_fmac_f32_e32 v218, v25, v8
	v_fmac_f32_e32 v219, v41, v8
	v_lshlrev_b32_e32 v5, 16, v168
	v_and_b32_e32 v6, 0xffff0000, v168
	v_fmac_f32_e32 v220, v24, v5
	v_fmac_f32_e32 v221, v40, v5
	v_fmac_f32_e32 v220, v25, v6
	v_fmac_f32_e32 v221, v41, v6
	v_lshlrev_b32_e32 v7, 16, v176
	v_and_b32_e32 v8, 0xffff0000, v176
	v_fmac_f32_e32 v222, v24, v7
	v_fmac_f32_e32 v223, v40, v7
	v_fmac_f32_e32 v222, v25, v8
	v_fmac_f32_e32 v223, v41, v8
	v_lshlrev_b32_e32 v5, 16, v184
	v_and_b32_e32 v6, 0xffff0000, v184
	v_fmac_f32_e32 v224, v24, v5
	v_fmac_f32_e32 v225, v40, v5
	v_fmac_f32_e32 v224, v25, v6
	v_fmac_f32_e32 v225, v41, v6
	v_lshlrev_b32_e32 v7, 16, v192
	v_and_b32_e32 v8, 0xffff0000, v192
	v_fmac_f32_e32 v226, v24, v7
	v_fmac_f32_e32 v227, v40, v7
	v_fmac_f32_e32 v226, v25, v8
	v_fmac_f32_e32 v227, v41, v8
	v_lshlrev_b32_e32 v5, 16, v200
	v_and_b32_e32 v6, 0xffff0000, v200
	v_fmac_f32_e32 v228, v24, v5
	v_fmac_f32_e32 v229, v40, v5
	v_fmac_f32_e32 v228, v25, v6
	v_fmac_f32_e32 v229, v41, v6
	v_lshlrev_b32_e32 v5, 16, v137
	v_and_b32_e32 v6, 0xffff0000, v137
	v_fmac_f32_e32 v212, v26, v5
	v_fmac_f32_e32 v213, v42, v5
	v_fmac_f32_e32 v212, v27, v6
	v_fmac_f32_e32 v213, v43, v6
	v_lshlrev_b32_e32 v7, 16, v145
	v_and_b32_e32 v8, 0xffff0000, v145
	v_fmac_f32_e32 v214, v26, v7
	v_fmac_f32_e32 v215, v42, v7
	v_fmac_f32_e32 v214, v27, v8
	v_fmac_f32_e32 v215, v43, v8
	v_lshlrev_b32_e32 v5, 16, v153
	v_and_b32_e32 v6, 0xffff0000, v153
	v_fmac_f32_e32 v216, v26, v5
	v_fmac_f32_e32 v217, v42, v5
	v_fmac_f32_e32 v216, v27, v6
	v_fmac_f32_e32 v217, v43, v6
	v_lshlrev_b32_e32 v7, 16, v161
	v_and_b32_e32 v8, 0xffff0000, v161
	v_fmac_f32_e32 v218, v26, v7
	v_fmac_f32_e32 v219, v42, v7
	v_fmac_f32_e32 v218, v27, v8
	v_fmac_f32_e32 v219, v43, v8
	v_lshlrev_b32_e32 v5, 16, v169
	v_and_b32_e32 v6, 0xffff0000, v169
	v_fmac_f32_e32 v220, v26, v5
	v_fmac_f32_e32 v221, v42, v5
	v_fmac_f32_e32 v220, v27, v6
	v_fmac_f32_e32 v221, v43, v6
	v_lshlrev_b32_e32 v7, 16, v177
	v_and_b32_e32 v8, 0xffff0000, v177
	v_fmac_f32_e32 v222, v26, v7
	v_fmac_f32_e32 v223, v42, v7
	v_fmac_f32_e32 v222, v27, v8
	v_fmac_f32_e32 v223, v43, v8
	v_lshlrev_b32_e32 v5, 16, v185
	v_and_b32_e32 v6, 0xffff0000, v185
	v_fmac_f32_e32 v224, v26, v5
	v_fmac_f32_e32 v225, v42, v5
	v_fmac_f32_e32 v224, v27, v6
	v_fmac_f32_e32 v225, v43, v6
	v_lshlrev_b32_e32 v7, 16, v193
	v_and_b32_e32 v8, 0xffff0000, v193
	v_fmac_f32_e32 v226, v26, v7
	v_fmac_f32_e32 v227, v42, v7
	v_fmac_f32_e32 v226, v27, v8
	v_fmac_f32_e32 v227, v43, v8
	v_lshlrev_b32_e32 v5, 16, v201
	v_and_b32_e32 v6, 0xffff0000, v201
	v_fmac_f32_e32 v228, v26, v5
	v_fmac_f32_e32 v229, v42, v5
	v_fmac_f32_e32 v228, v27, v6
	v_fmac_f32_e32 v229, v43, v6
	v_lshlrev_b32_e32 v5, 16, v138
	v_and_b32_e32 v6, 0xffff0000, v138
	v_fmac_f32_e32 v212, v28, v5
	v_fmac_f32_e32 v213, v44, v5
	v_fmac_f32_e32 v212, v29, v6
	v_fmac_f32_e32 v213, v45, v6
	v_lshlrev_b32_e32 v7, 16, v146
	v_and_b32_e32 v8, 0xffff0000, v146
	v_fmac_f32_e32 v214, v28, v7
	v_fmac_f32_e32 v215, v44, v7
	v_fmac_f32_e32 v214, v29, v8
	v_fmac_f32_e32 v215, v45, v8
	v_lshlrev_b32_e32 v5, 16, v154
	v_and_b32_e32 v6, 0xffff0000, v154
	v_fmac_f32_e32 v216, v28, v5
	v_fmac_f32_e32 v217, v44, v5
	v_fmac_f32_e32 v216, v29, v6
	v_fmac_f32_e32 v217, v45, v6
	v_lshlrev_b32_e32 v7, 16, v162
	v_and_b32_e32 v8, 0xffff0000, v162
	v_fmac_f32_e32 v218, v28, v7
	v_fmac_f32_e32 v219, v44, v7
	v_fmac_f32_e32 v218, v29, v8
	v_fmac_f32_e32 v219, v45, v8
	v_lshlrev_b32_e32 v5, 16, v170
	v_and_b32_e32 v6, 0xffff0000, v170
	v_fmac_f32_e32 v220, v28, v5
	v_fmac_f32_e32 v221, v44, v5
	v_fmac_f32_e32 v220, v29, v6
	v_fmac_f32_e32 v221, v45, v6
	v_lshlrev_b32_e32 v7, 16, v178
	v_and_b32_e32 v8, 0xffff0000, v178
	v_fmac_f32_e32 v222, v28, v7
	v_fmac_f32_e32 v223, v44, v7
	v_fmac_f32_e32 v222, v29, v8
	v_fmac_f32_e32 v223, v45, v8
	v_lshlrev_b32_e32 v5, 16, v186
	v_and_b32_e32 v6, 0xffff0000, v186
	v_fmac_f32_e32 v224, v28, v5
	v_fmac_f32_e32 v225, v44, v5
	v_fmac_f32_e32 v224, v29, v6
	v_fmac_f32_e32 v225, v45, v6
	v_lshlrev_b32_e32 v7, 16, v194
	v_and_b32_e32 v8, 0xffff0000, v194
	v_fmac_f32_e32 v226, v28, v7
	v_fmac_f32_e32 v227, v44, v7
	v_fmac_f32_e32 v226, v29, v8
	v_fmac_f32_e32 v227, v45, v8
	v_lshlrev_b32_e32 v5, 16, v202
	v_and_b32_e32 v6, 0xffff0000, v202
	v_fmac_f32_e32 v228, v28, v5
	v_fmac_f32_e32 v229, v44, v5
	v_fmac_f32_e32 v228, v29, v6
	v_fmac_f32_e32 v229, v45, v6
	v_lshlrev_b32_e32 v5, 16, v139
	v_and_b32_e32 v6, 0xffff0000, v139
	v_fmac_f32_e32 v212, v30, v5
	v_fmac_f32_e32 v213, v46, v5
	v_fmac_f32_e32 v212, v31, v6
	v_fmac_f32_e32 v213, v47, v6
	v_lshlrev_b32_e32 v7, 16, v147
	v_and_b32_e32 v8, 0xffff0000, v147
	v_fmac_f32_e32 v214, v30, v7
	v_fmac_f32_e32 v215, v46, v7
	v_fmac_f32_e32 v214, v31, v8
	v_fmac_f32_e32 v215, v47, v8
	v_lshlrev_b32_e32 v5, 16, v155
	v_and_b32_e32 v6, 0xffff0000, v155
	v_fmac_f32_e32 v216, v30, v5
	v_fmac_f32_e32 v217, v46, v5
	v_fmac_f32_e32 v216, v31, v6
	v_fmac_f32_e32 v217, v47, v6
	v_lshlrev_b32_e32 v7, 16, v163
	v_and_b32_e32 v8, 0xffff0000, v163
	v_fmac_f32_e32 v218, v30, v7
	v_fmac_f32_e32 v219, v46, v7
	v_fmac_f32_e32 v218, v31, v8
	v_fmac_f32_e32 v219, v47, v8
	v_lshlrev_b32_e32 v5, 16, v171
	v_and_b32_e32 v6, 0xffff0000, v171
	v_fmac_f32_e32 v220, v30, v5
	v_fmac_f32_e32 v221, v46, v5
	v_fmac_f32_e32 v220, v31, v6
	v_fmac_f32_e32 v221, v47, v6
	v_lshlrev_b32_e32 v7, 16, v179
	v_and_b32_e32 v8, 0xffff0000, v179
	v_fmac_f32_e32 v222, v30, v7
	v_fmac_f32_e32 v223, v46, v7
	v_fmac_f32_e32 v222, v31, v8
	v_fmac_f32_e32 v223, v47, v8
	v_lshlrev_b32_e32 v5, 16, v187
	v_and_b32_e32 v6, 0xffff0000, v187
	v_fmac_f32_e32 v224, v30, v5
	v_fmac_f32_e32 v225, v46, v5
	v_fmac_f32_e32 v224, v31, v6
	v_fmac_f32_e32 v225, v47, v6
	v_lshlrev_b32_e32 v7, 16, v195
	v_and_b32_e32 v8, 0xffff0000, v195
	v_fmac_f32_e32 v226, v30, v7
	v_fmac_f32_e32 v227, v46, v7
	v_fmac_f32_e32 v226, v31, v8
	v_fmac_f32_e32 v227, v47, v8
	v_lshlrev_b32_e32 v5, 16, v203
	v_and_b32_e32 v6, 0xffff0000, v203
	v_fmac_f32_e32 v228, v30, v5
	v_fmac_f32_e32 v229, v46, v5
	v_fmac_f32_e32 v228, v31, v6
	v_fmac_f32_e32 v229, v47, v6
	global_load_dwordx4 v[132:135], v1, s[28:29]
	global_load_dwordx4 v[136:139], v1, s[28:29] offset:16
	s_add_u32 s28, s28, 0x80000
	s_addc_u32 s29, s29, 0
	global_load_dwordx4 v[140:143], v1, s[28:29]
	global_load_dwordx4 v[144:147], v1, s[28:29] offset:16
	s_add_u32 s28, s28, 0x80000
	s_addc_u32 s29, s29, 0
	global_load_dwordx4 v[148:151], v1, s[28:29]
	global_load_dwordx4 v[152:155], v1, s[28:29] offset:16
	s_add_u32 s28, s28, 0x80000
	s_addc_u32 s29, s29, 0
	global_load_dwordx4 v[156:159], v1, s[28:29]
	global_load_dwordx4 v[160:163], v1, s[28:29] offset:16
	s_add_u32 s28, s28, 0x80000
	s_addc_u32 s29, s29, 0
	global_load_dwordx4 v[164:167], v1, s[28:29]
	global_load_dwordx4 v[168:171], v1, s[28:29] offset:16
	s_add_u32 s28, s28, 0x80000
	s_addc_u32 s29, s29, 0
	global_load_dwordx4 v[172:175], v1, s[28:29]
	global_load_dwordx4 v[176:179], v1, s[28:29] offset:16
	s_add_u32 s28, s28, 0x80000
	s_addc_u32 s29, s29, 0
	global_load_dwordx4 v[180:183], v1, s[28:29]
	global_load_dwordx4 v[184:187], v1, s[28:29] offset:16
	s_add_u32 s28, s28, 0x80000
	s_addc_u32 s29, s29, 0
	global_load_dwordx4 v[188:191], v1, s[28:29]
	global_load_dwordx4 v[192:195], v1, s[28:29] offset:16
	s_add_u32 s28, s28, 0x80000
	s_addc_u32 s29, s29, 0
	global_load_dwordx4 v[196:199], v1, s[28:29]
	global_load_dwordx4 v[200:203], v1, s[28:29] offset:16
	s_add_u32 s28, s28, 0x80000
	s_addc_u32 s29, s29, 0
	v_add_f32_dpp v212, v212, v212 quad_perm:[1,0,3,2] row_mask:0xf bank_mask:0xf
	v_add_f32_dpp v213, v213, v213 quad_perm:[1,0,3,2] row_mask:0xf bank_mask:0xf
	v_add_f32_dpp v214, v214, v214 quad_perm:[1,0,3,2] row_mask:0xf bank_mask:0xf
	v_add_f32_dpp v215, v215, v215 quad_perm:[1,0,3,2] row_mask:0xf bank_mask:0xf
	v_add_f32_dpp v216, v216, v216 quad_perm:[1,0,3,2] row_mask:0xf bank_mask:0xf
	v_add_f32_dpp v217, v217, v217 quad_perm:[1,0,3,2] row_mask:0xf bank_mask:0xf
	v_add_f32_dpp v218, v218, v218 quad_perm:[1,0,3,2] row_mask:0xf bank_mask:0xf
	v_add_f32_dpp v219, v219, v219 quad_perm:[1,0,3,2] row_mask:0xf bank_mask:0xf
	v_add_f32_dpp v220, v220, v220 quad_perm:[1,0,3,2] row_mask:0xf bank_mask:0xf
	v_add_f32_dpp v221, v221, v221 quad_perm:[1,0,3,2] row_mask:0xf bank_mask:0xf
	v_add_f32_dpp v222, v222, v222 quad_perm:[1,0,3,2] row_mask:0xf bank_mask:0xf
	v_add_f32_dpp v223, v223, v223 quad_perm:[1,0,3,2] row_mask:0xf bank_mask:0xf
	v_add_f32_dpp v224, v224, v224 quad_perm:[1,0,3,2] row_mask:0xf bank_mask:0xf
	v_add_f32_dpp v225, v225, v225 quad_perm:[1,0,3,2] row_mask:0xf bank_mask:0xf
	v_add_f32_dpp v226, v226, v226 quad_perm:[1,0,3,2] row_mask:0xf bank_mask:0xf
	v_add_f32_dpp v227, v227, v227 quad_perm:[1,0,3,2] row_mask:0xf bank_mask:0xf
	v_add_f32_dpp v228, v228, v228 quad_perm:[1,0,3,2] row_mask:0xf bank_mask:0xf
	v_add_f32_dpp v229, v229, v229 quad_perm:[1,0,3,2] row_mask:0xf bank_mask:0xf
	v_add_f32_dpp v212, v212, v212 quad_perm:[2,3,0,1] row_mask:0xf bank_mask:0xf
	v_add_f32_dpp v213, v213, v213 quad_perm:[2,3,0,1] row_mask:0xf bank_mask:0xf
	v_add_f32_dpp v214, v214, v214 quad_perm:[2,3,0,1] row_mask:0xf bank_mask:0xf
	v_add_f32_dpp v215, v215, v215 quad_perm:[2,3,0,1] row_mask:0xf bank_mask:0xf
	v_add_f32_dpp v216, v216, v216 quad_perm:[2,3,0,1] row_mask:0xf bank_mask:0xf
	v_add_f32_dpp v217, v217, v217 quad_perm:[2,3,0,1] row_mask:0xf bank_mask:0xf
	v_add_f32_dpp v218, v218, v218 quad_perm:[2,3,0,1] row_mask:0xf bank_mask:0xf
	v_add_f32_dpp v219, v219, v219 quad_perm:[2,3,0,1] row_mask:0xf bank_mask:0xf
	v_add_f32_dpp v220, v220, v220 quad_perm:[2,3,0,1] row_mask:0xf bank_mask:0xf
	v_add_f32_dpp v221, v221, v221 quad_perm:[2,3,0,1] row_mask:0xf bank_mask:0xf
	v_add_f32_dpp v222, v222, v222 quad_perm:[2,3,0,1] row_mask:0xf bank_mask:0xf
	v_add_f32_dpp v223, v223, v223 quad_perm:[2,3,0,1] row_mask:0xf bank_mask:0xf
	v_add_f32_dpp v224, v224, v224 quad_perm:[2,3,0,1] row_mask:0xf bank_mask:0xf
	v_add_f32_dpp v225, v225, v225 quad_perm:[2,3,0,1] row_mask:0xf bank_mask:0xf
	v_add_f32_dpp v226, v226, v226 quad_perm:[2,3,0,1] row_mask:0xf bank_mask:0xf
	v_add_f32_dpp v227, v227, v227 quad_perm:[2,3,0,1] row_mask:0xf bank_mask:0xf
	v_add_f32_dpp v228, v228, v228 quad_perm:[2,3,0,1] row_mask:0xf bank_mask:0xf
	v_add_f32_dpp v229, v229, v229 quad_perm:[2,3,0,1] row_mask:0xf bank_mask:0xf
	v_add_f32_dpp v212, v212, v212 row_half_mirror row_mask:0xf bank_mask:0xf
	v_add_f32_dpp v213, v213, v213 row_half_mirror row_mask:0xf bank_mask:0xf
	v_add_f32_dpp v214, v214, v214 row_half_mirror row_mask:0xf bank_mask:0xf
	v_add_f32_dpp v215, v215, v215 row_half_mirror row_mask:0xf bank_mask:0xf
	v_add_f32_dpp v216, v216, v216 row_half_mirror row_mask:0xf bank_mask:0xf
	v_add_f32_dpp v217, v217, v217 row_half_mirror row_mask:0xf bank_mask:0xf
	v_add_f32_dpp v218, v218, v218 row_half_mirror row_mask:0xf bank_mask:0xf
	v_add_f32_dpp v219, v219, v219 row_half_mirror row_mask:0xf bank_mask:0xf
	v_add_f32_dpp v220, v220, v220 row_half_mirror row_mask:0xf bank_mask:0xf
	v_add_f32_dpp v221, v221, v221 row_half_mirror row_mask:0xf bank_mask:0xf
	v_add_f32_dpp v222, v222, v222 row_half_mirror row_mask:0xf bank_mask:0xf
	v_add_f32_dpp v223, v223, v223 row_half_mirror row_mask:0xf bank_mask:0xf
	v_add_f32_dpp v224, v224, v224 row_half_mirror row_mask:0xf bank_mask:0xf
	v_add_f32_dpp v225, v225, v225 row_half_mirror row_mask:0xf bank_mask:0xf
	v_add_f32_dpp v226, v226, v226 row_half_mirror row_mask:0xf bank_mask:0xf
	v_add_f32_dpp v227, v227, v227 row_half_mirror row_mask:0xf bank_mask:0xf
	v_add_f32_dpp v228, v228, v228 row_half_mirror row_mask:0xf bank_mask:0xf
	v_add_f32_dpp v229, v229, v229 row_half_mirror row_mask:0xf bank_mask:0xf
	v_add_f32_dpp v212, v212, v212 row_mirror row_mask:0xf bank_mask:0xf
	v_add_f32_dpp v213, v213, v213 row_mirror row_mask:0xf bank_mask:0xf
	v_add_f32_dpp v214, v214, v214 row_mirror row_mask:0xf bank_mask:0xf
	v_add_f32_dpp v215, v215, v215 row_mirror row_mask:0xf bank_mask:0xf
	v_add_f32_dpp v216, v216, v216 row_mirror row_mask:0xf bank_mask:0xf
	v_add_f32_dpp v217, v217, v217 row_mirror row_mask:0xf bank_mask:0xf
	v_add_f32_dpp v218, v218, v218 row_mirror row_mask:0xf bank_mask:0xf
	v_add_f32_dpp v219, v219, v219 row_mirror row_mask:0xf bank_mask:0xf
	v_add_f32_dpp v220, v220, v220 row_mirror row_mask:0xf bank_mask:0xf
	v_add_f32_dpp v221, v221, v221 row_mirror row_mask:0xf bank_mask:0xf
	v_add_f32_dpp v222, v222, v222 row_mirror row_mask:0xf bank_mask:0xf
	v_add_f32_dpp v223, v223, v223 row_mirror row_mask:0xf bank_mask:0xf
	v_add_f32_dpp v224, v224, v224 row_mirror row_mask:0xf bank_mask:0xf
	v_add_f32_dpp v225, v225, v225 row_mirror row_mask:0xf bank_mask:0xf
	v_add_f32_dpp v226, v226, v226 row_mirror row_mask:0xf bank_mask:0xf
	v_add_f32_dpp v227, v227, v227 row_mirror row_mask:0xf bank_mask:0xf
	v_add_f32_dpp v228, v228, v228 row_mirror row_mask:0xf bank_mask:0xf
	v_add_f32_dpp v229, v229, v229 row_mirror row_mask:0xf bank_mask:0xf
	v_add_f32_dpp v212, v212, v212 row_bcast:15 row_mask:0xa bank_mask:0xf
	v_add_f32_dpp v213, v213, v213 row_bcast:15 row_mask:0xa bank_mask:0xf
	v_add_f32_dpp v214, v214, v214 row_bcast:15 row_mask:0xa bank_mask:0xf
	v_add_f32_dpp v215, v215, v215 row_bcast:15 row_mask:0xa bank_mask:0xf
	v_add_f32_dpp v216, v216, v216 row_bcast:15 row_mask:0xa bank_mask:0xf
	v_add_f32_dpp v217, v217, v217 row_bcast:15 row_mask:0xa bank_mask:0xf
	v_add_f32_dpp v218, v218, v218 row_bcast:15 row_mask:0xa bank_mask:0xf
	v_add_f32_dpp v219, v219, v219 row_bcast:15 row_mask:0xa bank_mask:0xf
	v_add_f32_dpp v220, v220, v220 row_bcast:15 row_mask:0xa bank_mask:0xf
	v_add_f32_dpp v221, v221, v221 row_bcast:15 row_mask:0xa bank_mask:0xf
	v_add_f32_dpp v222, v222, v222 row_bcast:15 row_mask:0xa bank_mask:0xf
	v_add_f32_dpp v223, v223, v223 row_bcast:15 row_mask:0xa bank_mask:0xf
	v_add_f32_dpp v224, v224, v224 row_bcast:15 row_mask:0xa bank_mask:0xf
	v_add_f32_dpp v225, v225, v225 row_bcast:15 row_mask:0xa bank_mask:0xf
	v_add_f32_dpp v226, v226, v226 row_bcast:15 row_mask:0xa bank_mask:0xf
	v_add_f32_dpp v227, v227, v227 row_bcast:15 row_mask:0xa bank_mask:0xf
	v_add_f32_dpp v228, v228, v228 row_bcast:15 row_mask:0xa bank_mask:0xf
	v_add_f32_dpp v229, v229, v229 row_bcast:15 row_mask:0xa bank_mask:0xf
	v_add_f32_dpp v212, v212, v212 row_bcast:31 row_mask:0xc bank_mask:0xf
	v_add_f32_dpp v213, v213, v213 row_bcast:31 row_mask:0xc bank_mask:0xf
	v_add_f32_dpp v214, v214, v214 row_bcast:31 row_mask:0xc bank_mask:0xf
	v_add_f32_dpp v215, v215, v215 row_bcast:31 row_mask:0xc bank_mask:0xf
	v_add_f32_dpp v216, v216, v216 row_bcast:31 row_mask:0xc bank_mask:0xf
	v_add_f32_dpp v217, v217, v217 row_bcast:31 row_mask:0xc bank_mask:0xf
	v_add_f32_dpp v218, v218, v218 row_bcast:31 row_mask:0xc bank_mask:0xf
	v_add_f32_dpp v219, v219, v219 row_bcast:31 row_mask:0xc bank_mask:0xf
	v_add_f32_dpp v220, v220, v220 row_bcast:31 row_mask:0xc bank_mask:0xf
	v_add_f32_dpp v221, v221, v221 row_bcast:31 row_mask:0xc bank_mask:0xf
	v_add_f32_dpp v222, v222, v222 row_bcast:31 row_mask:0xc bank_mask:0xf
	v_add_f32_dpp v223, v223, v223 row_bcast:31 row_mask:0xc bank_mask:0xf
	v_add_f32_dpp v224, v224, v224 row_bcast:31 row_mask:0xc bank_mask:0xf
	v_add_f32_dpp v225, v225, v225 row_bcast:31 row_mask:0xc bank_mask:0xf
	v_add_f32_dpp v226, v226, v226 row_bcast:31 row_mask:0xc bank_mask:0xf
	v_add_f32_dpp v227, v227, v227 row_bcast:31 row_mask:0xc bank_mask:0xf
	v_add_f32_dpp v228, v228, v228 row_bcast:31 row_mask:0xc bank_mask:0xf
	v_add_f32_dpp v229, v229, v229 row_bcast:31 row_mask:0xc bank_mask:0xf
	s_nop 0
	v_readlane_b32 s32, v212, 63
	v_readlane_b32 s33, v213, 63
	v_readlane_b32 s40, v214, 63
	v_readlane_b32 s41, v215, 63
	v_readlane_b32 s46, v216, 63
	v_readlane_b32 s47, v217, 63
	v_readlane_b32 s51, v218, 63
	v_readlane_b32 s57, v219, 63
	v_readlane_b32 s58, v220, 63
	v_readlane_b32 s59, v221, 63
	v_readlane_b32 s60, v222, 63
	v_readlane_b32 s61, v223, 63
	v_readlane_b32 s62, v224, 63
	v_readlane_b32 s63, v225, 63
	v_readlane_b32 s70, v226, 63
	v_readlane_b32 s71, v227, 63
	v_readlane_b32 s74, v228, 63
	v_readlane_b32 s75, v229, 63
	s_nop 1
	v_writelane_b32 v9, s32, 0
	v_writelane_b32 v9, s33, 1
	v_writelane_b32 v9, s40, 2
	v_writelane_b32 v9, s41, 3
	v_writelane_b32 v9, s46, 4
	v_writelane_b32 v9, s47, 5
	v_writelane_b32 v9, s51, 6
	v_writelane_b32 v9, s57, 7
	v_writelane_b32 v9, s58, 8
	v_writelane_b32 v9, s59, 9
	v_writelane_b32 v9, s60, 10
	v_writelane_b32 v9, s61, 11
	v_writelane_b32 v9, s62, 12
	v_writelane_b32 v9, s63, 13
	v_writelane_b32 v9, s70, 14
	v_writelane_b32 v9, s71, 15
	v_writelane_b32 v9, s74, 16
	v_writelane_b32 v9, s75, 17
	s_mul_i32 s91, s3, 11264
	s_add_i32 s91, s91, s5
	s_add_u32 s8, s0, 0x3e00000
	s_addc_u32 s9, s1, 0
	v_add_u32_e32 v15, s91, v14
	v_lshlrev_b32_e32 v15, 2, v15
	s_mov_b64 exec, 0x3ffff
	global_store_dword v15, v9, s[8:9]
	s_mov_b64 exec, -1
	s_waitcnt vmcnt(0)
	v_lshlrev_b32_e32 v5, 16, v132
	v_and_b32_e32 v6, 0xffff0000, v132
	v_mul_f32_e32 v212, v16, v5
	v_mul_f32_e32 v213, v32, v5
	v_fmac_f32_e32 v212, v17, v6
	v_fmac_f32_e32 v213, v33, v6
	v_lshlrev_b32_e32 v7, 16, v140
	v_and_b32_e32 v8, 0xffff0000, v140
	v_mul_f32_e32 v214, v16, v7
	v_mul_f32_e32 v215, v32, v7
	v_fmac_f32_e32 v214, v17, v8
	v_fmac_f32_e32 v215, v33, v8
	v_lshlrev_b32_e32 v5, 16, v148
	v_and_b32_e32 v6, 0xffff0000, v148
	v_mul_f32_e32 v216, v16, v5
	v_mul_f32_e32 v217, v32, v5
	v_fmac_f32_e32 v216, v17, v6
	v_fmac_f32_e32 v217, v33, v6
	v_lshlrev_b32_e32 v7, 16, v156
	v_and_b32_e32 v8, 0xffff0000, v156
	v_mul_f32_e32 v218, v16, v7
	v_mul_f32_e32 v219, v32, v7
	v_fmac_f32_e32 v218, v17, v8
	v_fmac_f32_e32 v219, v33, v8
	v_lshlrev_b32_e32 v5, 16, v164
	v_and_b32_e32 v6, 0xffff0000, v164
	v_mul_f32_e32 v220, v16, v5
	v_mul_f32_e32 v221, v32, v5
	v_fmac_f32_e32 v220, v17, v6
	v_fmac_f32_e32 v221, v33, v6
	v_lshlrev_b32_e32 v7, 16, v172
	v_and_b32_e32 v8, 0xffff0000, v172
	v_mul_f32_e32 v222, v16, v7
	v_mul_f32_e32 v223, v32, v7
	v_fmac_f32_e32 v222, v17, v8
	v_fmac_f32_e32 v223, v33, v8
	v_lshlrev_b32_e32 v5, 16, v180
	v_and_b32_e32 v6, 0xffff0000, v180
	v_mul_f32_e32 v224, v16, v5
	v_mul_f32_e32 v225, v32, v5
	v_fmac_f32_e32 v224, v17, v6
	v_fmac_f32_e32 v225, v33, v6
	v_lshlrev_b32_e32 v7, 16, v188
	v_and_b32_e32 v8, 0xffff0000, v188
	v_mul_f32_e32 v226, v16, v7
	v_mul_f32_e32 v227, v32, v7
	v_fmac_f32_e32 v226, v17, v8
	v_fmac_f32_e32 v227, v33, v8
	v_lshlrev_b32_e32 v5, 16, v196
	v_and_b32_e32 v6, 0xffff0000, v196
	v_mul_f32_e32 v228, v16, v5
	v_mul_f32_e32 v229, v32, v5
	v_fmac_f32_e32 v228, v17, v6
	v_fmac_f32_e32 v229, v33, v6
	v_lshlrev_b32_e32 v5, 16, v133
	v_and_b32_e32 v6, 0xffff0000, v133
	v_fmac_f32_e32 v212, v18, v5
	v_fmac_f32_e32 v213, v34, v5
	v_fmac_f32_e32 v212, v19, v6
	v_fmac_f32_e32 v213, v35, v6
	v_lshlrev_b32_e32 v7, 16, v141
	v_and_b32_e32 v8, 0xffff0000, v141
	v_fmac_f32_e32 v214, v18, v7
	v_fmac_f32_e32 v215, v34, v7
	v_fmac_f32_e32 v214, v19, v8
	v_fmac_f32_e32 v215, v35, v8
	v_lshlrev_b32_e32 v5, 16, v149
	v_and_b32_e32 v6, 0xffff0000, v149
	v_fmac_f32_e32 v216, v18, v5
	v_fmac_f32_e32 v217, v34, v5
	v_fmac_f32_e32 v216, v19, v6
	v_fmac_f32_e32 v217, v35, v6
	v_lshlrev_b32_e32 v7, 16, v157
	v_and_b32_e32 v8, 0xffff0000, v157
	v_fmac_f32_e32 v218, v18, v7
	v_fmac_f32_e32 v219, v34, v7
	v_fmac_f32_e32 v218, v19, v8
	v_fmac_f32_e32 v219, v35, v8
	v_lshlrev_b32_e32 v5, 16, v165
	v_and_b32_e32 v6, 0xffff0000, v165
	v_fmac_f32_e32 v220, v18, v5
	v_fmac_f32_e32 v221, v34, v5
	v_fmac_f32_e32 v220, v19, v6
	v_fmac_f32_e32 v221, v35, v6
	v_lshlrev_b32_e32 v7, 16, v173
	v_and_b32_e32 v8, 0xffff0000, v173
	v_fmac_f32_e32 v222, v18, v7
	v_fmac_f32_e32 v223, v34, v7
	v_fmac_f32_e32 v222, v19, v8
	v_fmac_f32_e32 v223, v35, v8
	v_lshlrev_b32_e32 v5, 16, v181
	v_and_b32_e32 v6, 0xffff0000, v181
	v_fmac_f32_e32 v224, v18, v5
	v_fmac_f32_e32 v225, v34, v5
	v_fmac_f32_e32 v224, v19, v6
	v_fmac_f32_e32 v225, v35, v6
	v_lshlrev_b32_e32 v7, 16, v189
	v_and_b32_e32 v8, 0xffff0000, v189
	v_fmac_f32_e32 v226, v18, v7
	v_fmac_f32_e32 v227, v34, v7
	v_fmac_f32_e32 v226, v19, v8
	v_fmac_f32_e32 v227, v35, v8
	v_lshlrev_b32_e32 v5, 16, v197
	v_and_b32_e32 v6, 0xffff0000, v197
	v_fmac_f32_e32 v228, v18, v5
	v_fmac_f32_e32 v229, v34, v5
	v_fmac_f32_e32 v228, v19, v6
	v_fmac_f32_e32 v229, v35, v6
	v_lshlrev_b32_e32 v5, 16, v134
	v_and_b32_e32 v6, 0xffff0000, v134
	v_fmac_f32_e32 v212, v20, v5
	v_fmac_f32_e32 v213, v36, v5
	v_fmac_f32_e32 v212, v21, v6
	v_fmac_f32_e32 v213, v37, v6
	v_lshlrev_b32_e32 v7, 16, v142
	v_and_b32_e32 v8, 0xffff0000, v142
	v_fmac_f32_e32 v214, v20, v7
	v_fmac_f32_e32 v215, v36, v7
	v_fmac_f32_e32 v214, v21, v8
	v_fmac_f32_e32 v215, v37, v8
	v_lshlrev_b32_e32 v5, 16, v150
	v_and_b32_e32 v6, 0xffff0000, v150
	v_fmac_f32_e32 v216, v20, v5
	v_fmac_f32_e32 v217, v36, v5
	v_fmac_f32_e32 v216, v21, v6
	v_fmac_f32_e32 v217, v37, v6
	v_lshlrev_b32_e32 v7, 16, v158
	v_and_b32_e32 v8, 0xffff0000, v158
	v_fmac_f32_e32 v218, v20, v7
	v_fmac_f32_e32 v219, v36, v7
	v_fmac_f32_e32 v218, v21, v8
	v_fmac_f32_e32 v219, v37, v8
	v_lshlrev_b32_e32 v5, 16, v166
	v_and_b32_e32 v6, 0xffff0000, v166
	v_fmac_f32_e32 v220, v20, v5
	v_fmac_f32_e32 v221, v36, v5
	v_fmac_f32_e32 v220, v21, v6
	v_fmac_f32_e32 v221, v37, v6
	v_lshlrev_b32_e32 v7, 16, v174
	v_and_b32_e32 v8, 0xffff0000, v174
	v_fmac_f32_e32 v222, v20, v7
	v_fmac_f32_e32 v223, v36, v7
	v_fmac_f32_e32 v222, v21, v8
	v_fmac_f32_e32 v223, v37, v8
	v_lshlrev_b32_e32 v5, 16, v182
	v_and_b32_e32 v6, 0xffff0000, v182
	v_fmac_f32_e32 v224, v20, v5
	v_fmac_f32_e32 v225, v36, v5
	v_fmac_f32_e32 v224, v21, v6
	v_fmac_f32_e32 v225, v37, v6
	v_lshlrev_b32_e32 v7, 16, v190
	v_and_b32_e32 v8, 0xffff0000, v190
	v_fmac_f32_e32 v226, v20, v7
	v_fmac_f32_e32 v227, v36, v7
	v_fmac_f32_e32 v226, v21, v8
	v_fmac_f32_e32 v227, v37, v8
	v_lshlrev_b32_e32 v5, 16, v198
	v_and_b32_e32 v6, 0xffff0000, v198
	v_fmac_f32_e32 v228, v20, v5
	v_fmac_f32_e32 v229, v36, v5
	v_fmac_f32_e32 v228, v21, v6
	v_fmac_f32_e32 v229, v37, v6
	v_lshlrev_b32_e32 v5, 16, v135
	v_and_b32_e32 v6, 0xffff0000, v135
	v_fmac_f32_e32 v212, v22, v5
	v_fmac_f32_e32 v213, v38, v5
	v_fmac_f32_e32 v212, v23, v6
	v_fmac_f32_e32 v213, v39, v6
	v_lshlrev_b32_e32 v7, 16, v143
	v_and_b32_e32 v8, 0xffff0000, v143
	v_fmac_f32_e32 v214, v22, v7
	v_fmac_f32_e32 v215, v38, v7
	v_fmac_f32_e32 v214, v23, v8
	v_fmac_f32_e32 v215, v39, v8
	v_lshlrev_b32_e32 v5, 16, v151
	v_and_b32_e32 v6, 0xffff0000, v151
	v_fmac_f32_e32 v216, v22, v5
	v_fmac_f32_e32 v217, v38, v5
	v_fmac_f32_e32 v216, v23, v6
	v_fmac_f32_e32 v217, v39, v6
	v_lshlrev_b32_e32 v7, 16, v159
	v_and_b32_e32 v8, 0xffff0000, v159
	v_fmac_f32_e32 v218, v22, v7
	v_fmac_f32_e32 v219, v38, v7
	v_fmac_f32_e32 v218, v23, v8
	v_fmac_f32_e32 v219, v39, v8
	v_lshlrev_b32_e32 v5, 16, v167
	v_and_b32_e32 v6, 0xffff0000, v167
	v_fmac_f32_e32 v220, v22, v5
	v_fmac_f32_e32 v221, v38, v5
	v_fmac_f32_e32 v220, v23, v6
	v_fmac_f32_e32 v221, v39, v6
	v_lshlrev_b32_e32 v7, 16, v175
	v_and_b32_e32 v8, 0xffff0000, v175
	v_fmac_f32_e32 v222, v22, v7
	v_fmac_f32_e32 v223, v38, v7
	v_fmac_f32_e32 v222, v23, v8
	v_fmac_f32_e32 v223, v39, v8
	v_lshlrev_b32_e32 v5, 16, v183
	v_and_b32_e32 v6, 0xffff0000, v183
	v_fmac_f32_e32 v224, v22, v5
	v_fmac_f32_e32 v225, v38, v5
	v_fmac_f32_e32 v224, v23, v6
	v_fmac_f32_e32 v225, v39, v6
	v_lshlrev_b32_e32 v7, 16, v191
	v_and_b32_e32 v8, 0xffff0000, v191
	v_fmac_f32_e32 v226, v22, v7
	v_fmac_f32_e32 v227, v38, v7
	v_fmac_f32_e32 v226, v23, v8
	v_fmac_f32_e32 v227, v39, v8
	v_lshlrev_b32_e32 v5, 16, v199
	v_and_b32_e32 v6, 0xffff0000, v199
	v_fmac_f32_e32 v228, v22, v5
	v_fmac_f32_e32 v229, v38, v5
	v_fmac_f32_e32 v228, v23, v6
	v_fmac_f32_e32 v229, v39, v6
	v_lshlrev_b32_e32 v5, 16, v136
	v_and_b32_e32 v6, 0xffff0000, v136
	v_fmac_f32_e32 v212, v24, v5
	v_fmac_f32_e32 v213, v40, v5
	v_fmac_f32_e32 v212, v25, v6
	v_fmac_f32_e32 v213, v41, v6
	v_lshlrev_b32_e32 v7, 16, v144
	v_and_b32_e32 v8, 0xffff0000, v144
	v_fmac_f32_e32 v214, v24, v7
	v_fmac_f32_e32 v215, v40, v7
	v_fmac_f32_e32 v214, v25, v8
	v_fmac_f32_e32 v215, v41, v8
	v_lshlrev_b32_e32 v5, 16, v152
	v_and_b32_e32 v6, 0xffff0000, v152
	v_fmac_f32_e32 v216, v24, v5
	v_fmac_f32_e32 v217, v40, v5
	v_fmac_f32_e32 v216, v25, v6
	v_fmac_f32_e32 v217, v41, v6
	v_lshlrev_b32_e32 v7, 16, v160
	v_and_b32_e32 v8, 0xffff0000, v160
	v_fmac_f32_e32 v218, v24, v7
	v_fmac_f32_e32 v219, v40, v7
	v_fmac_f32_e32 v218, v25, v8
	v_fmac_f32_e32 v219, v41, v8
	v_lshlrev_b32_e32 v5, 16, v168
	v_and_b32_e32 v6, 0xffff0000, v168
	v_fmac_f32_e32 v220, v24, v5
	v_fmac_f32_e32 v221, v40, v5
	v_fmac_f32_e32 v220, v25, v6
	v_fmac_f32_e32 v221, v41, v6
	v_lshlrev_b32_e32 v7, 16, v176
	v_and_b32_e32 v8, 0xffff0000, v176
	v_fmac_f32_e32 v222, v24, v7
	v_fmac_f32_e32 v223, v40, v7
	v_fmac_f32_e32 v222, v25, v8
	v_fmac_f32_e32 v223, v41, v8
	v_lshlrev_b32_e32 v5, 16, v184
	v_and_b32_e32 v6, 0xffff0000, v184
	v_fmac_f32_e32 v224, v24, v5
	v_fmac_f32_e32 v225, v40, v5
	v_fmac_f32_e32 v224, v25, v6
	v_fmac_f32_e32 v225, v41, v6
	v_lshlrev_b32_e32 v7, 16, v192
	v_and_b32_e32 v8, 0xffff0000, v192
	v_fmac_f32_e32 v226, v24, v7
	v_fmac_f32_e32 v227, v40, v7
	v_fmac_f32_e32 v226, v25, v8
	v_fmac_f32_e32 v227, v41, v8
	v_lshlrev_b32_e32 v5, 16, v200
	v_and_b32_e32 v6, 0xffff0000, v200
	v_fmac_f32_e32 v228, v24, v5
	v_fmac_f32_e32 v229, v40, v5
	v_fmac_f32_e32 v228, v25, v6
	v_fmac_f32_e32 v229, v41, v6
	v_lshlrev_b32_e32 v5, 16, v137
	v_and_b32_e32 v6, 0xffff0000, v137
	v_fmac_f32_e32 v212, v26, v5
	v_fmac_f32_e32 v213, v42, v5
	v_fmac_f32_e32 v212, v27, v6
	v_fmac_f32_e32 v213, v43, v6
	v_lshlrev_b32_e32 v7, 16, v145
	v_and_b32_e32 v8, 0xffff0000, v145
	v_fmac_f32_e32 v214, v26, v7
	v_fmac_f32_e32 v215, v42, v7
	v_fmac_f32_e32 v214, v27, v8
	v_fmac_f32_e32 v215, v43, v8
	v_lshlrev_b32_e32 v5, 16, v153
	v_and_b32_e32 v6, 0xffff0000, v153
	v_fmac_f32_e32 v216, v26, v5
	v_fmac_f32_e32 v217, v42, v5
	v_fmac_f32_e32 v216, v27, v6
	v_fmac_f32_e32 v217, v43, v6
	v_lshlrev_b32_e32 v7, 16, v161
	v_and_b32_e32 v8, 0xffff0000, v161
	v_fmac_f32_e32 v218, v26, v7
	v_fmac_f32_e32 v219, v42, v7
	v_fmac_f32_e32 v218, v27, v8
	v_fmac_f32_e32 v219, v43, v8
	v_lshlrev_b32_e32 v5, 16, v169
	v_and_b32_e32 v6, 0xffff0000, v169
	v_fmac_f32_e32 v220, v26, v5
	v_fmac_f32_e32 v221, v42, v5
	v_fmac_f32_e32 v220, v27, v6
	v_fmac_f32_e32 v221, v43, v6
	v_lshlrev_b32_e32 v7, 16, v177
	v_and_b32_e32 v8, 0xffff0000, v177
	v_fmac_f32_e32 v222, v26, v7
	v_fmac_f32_e32 v223, v42, v7
	v_fmac_f32_e32 v222, v27, v8
	v_fmac_f32_e32 v223, v43, v8
	v_lshlrev_b32_e32 v5, 16, v185
	v_and_b32_e32 v6, 0xffff0000, v185
	v_fmac_f32_e32 v224, v26, v5
	v_fmac_f32_e32 v225, v42, v5
	v_fmac_f32_e32 v224, v27, v6
	v_fmac_f32_e32 v225, v43, v6
	v_lshlrev_b32_e32 v7, 16, v193
	v_and_b32_e32 v8, 0xffff0000, v193
	v_fmac_f32_e32 v226, v26, v7
	v_fmac_f32_e32 v227, v42, v7
	v_fmac_f32_e32 v226, v27, v8
	v_fmac_f32_e32 v227, v43, v8
	v_lshlrev_b32_e32 v5, 16, v201
	v_and_b32_e32 v6, 0xffff0000, v201
	v_fmac_f32_e32 v228, v26, v5
	v_fmac_f32_e32 v229, v42, v5
	v_fmac_f32_e32 v228, v27, v6
	v_fmac_f32_e32 v229, v43, v6
	v_lshlrev_b32_e32 v5, 16, v138
	v_and_b32_e32 v6, 0xffff0000, v138
	v_fmac_f32_e32 v212, v28, v5
	v_fmac_f32_e32 v213, v44, v5
	v_fmac_f32_e32 v212, v29, v6
	v_fmac_f32_e32 v213, v45, v6
	v_lshlrev_b32_e32 v7, 16, v146
	v_and_b32_e32 v8, 0xffff0000, v146
	v_fmac_f32_e32 v214, v28, v7
	v_fmac_f32_e32 v215, v44, v7
	v_fmac_f32_e32 v214, v29, v8
	v_fmac_f32_e32 v215, v45, v8
	v_lshlrev_b32_e32 v5, 16, v154
	v_and_b32_e32 v6, 0xffff0000, v154
	v_fmac_f32_e32 v216, v28, v5
	v_fmac_f32_e32 v217, v44, v5
	v_fmac_f32_e32 v216, v29, v6
	v_fmac_f32_e32 v217, v45, v6
	v_lshlrev_b32_e32 v7, 16, v162
	v_and_b32_e32 v8, 0xffff0000, v162
	v_fmac_f32_e32 v218, v28, v7
	v_fmac_f32_e32 v219, v44, v7
	v_fmac_f32_e32 v218, v29, v8
	v_fmac_f32_e32 v219, v45, v8
	v_lshlrev_b32_e32 v5, 16, v170
	v_and_b32_e32 v6, 0xffff0000, v170
	v_fmac_f32_e32 v220, v28, v5
	v_fmac_f32_e32 v221, v44, v5
	v_fmac_f32_e32 v220, v29, v6
	v_fmac_f32_e32 v221, v45, v6
	v_lshlrev_b32_e32 v7, 16, v178
	v_and_b32_e32 v8, 0xffff0000, v178
	v_fmac_f32_e32 v222, v28, v7
	v_fmac_f32_e32 v223, v44, v7
	v_fmac_f32_e32 v222, v29, v8
	v_fmac_f32_e32 v223, v45, v8
	v_lshlrev_b32_e32 v5, 16, v186
	v_and_b32_e32 v6, 0xffff0000, v186
	v_fmac_f32_e32 v224, v28, v5
	v_fmac_f32_e32 v225, v44, v5
	v_fmac_f32_e32 v224, v29, v6
	v_fmac_f32_e32 v225, v45, v6
	v_lshlrev_b32_e32 v7, 16, v194
	v_and_b32_e32 v8, 0xffff0000, v194
	v_fmac_f32_e32 v226, v28, v7
	v_fmac_f32_e32 v227, v44, v7
	v_fmac_f32_e32 v226, v29, v8
	v_fmac_f32_e32 v227, v45, v8
	v_lshlrev_b32_e32 v5, 16, v202
	v_and_b32_e32 v6, 0xffff0000, v202
	v_fmac_f32_e32 v228, v28, v5
	v_fmac_f32_e32 v229, v44, v5
	v_fmac_f32_e32 v228, v29, v6
	v_fmac_f32_e32 v229, v45, v6
	v_lshlrev_b32_e32 v5, 16, v139
	v_and_b32_e32 v6, 0xffff0000, v139
	v_fmac_f32_e32 v212, v30, v5
	v_fmac_f32_e32 v213, v46, v5
	v_fmac_f32_e32 v212, v31, v6
	v_fmac_f32_e32 v213, v47, v6
	v_lshlrev_b32_e32 v7, 16, v147
	v_and_b32_e32 v8, 0xffff0000, v147
	v_fmac_f32_e32 v214, v30, v7
	v_fmac_f32_e32 v215, v46, v7
	v_fmac_f32_e32 v214, v31, v8
	v_fmac_f32_e32 v215, v47, v8
	v_lshlrev_b32_e32 v5, 16, v155
	v_and_b32_e32 v6, 0xffff0000, v155
	v_fmac_f32_e32 v216, v30, v5
	v_fmac_f32_e32 v217, v46, v5
	v_fmac_f32_e32 v216, v31, v6
	v_fmac_f32_e32 v217, v47, v6
	v_lshlrev_b32_e32 v7, 16, v163
	v_and_b32_e32 v8, 0xffff0000, v163
	v_fmac_f32_e32 v218, v30, v7
	v_fmac_f32_e32 v219, v46, v7
	v_fmac_f32_e32 v218, v31, v8
	v_fmac_f32_e32 v219, v47, v8
	v_lshlrev_b32_e32 v5, 16, v171
	v_and_b32_e32 v6, 0xffff0000, v171
	v_fmac_f32_e32 v220, v30, v5
	v_fmac_f32_e32 v221, v46, v5
	v_fmac_f32_e32 v220, v31, v6
	v_fmac_f32_e32 v221, v47, v6
	v_lshlrev_b32_e32 v7, 16, v179
	v_and_b32_e32 v8, 0xffff0000, v179
	v_fmac_f32_e32 v222, v30, v7
	v_fmac_f32_e32 v223, v46, v7
	v_fmac_f32_e32 v222, v31, v8
	v_fmac_f32_e32 v223, v47, v8
	v_lshlrev_b32_e32 v5, 16, v187
	v_and_b32_e32 v6, 0xffff0000, v187
	v_fmac_f32_e32 v224, v30, v5
	v_fmac_f32_e32 v225, v46, v5
	v_fmac_f32_e32 v224, v31, v6
	v_fmac_f32_e32 v225, v47, v6
	v_lshlrev_b32_e32 v7, 16, v195
	v_and_b32_e32 v8, 0xffff0000, v195
	v_fmac_f32_e32 v226, v30, v7
	v_fmac_f32_e32 v227, v46, v7
	v_fmac_f32_e32 v226, v31, v8
	v_fmac_f32_e32 v227, v47, v8
	v_lshlrev_b32_e32 v5, 16, v203
	v_and_b32_e32 v6, 0xffff0000, v203
	v_fmac_f32_e32 v228, v30, v5
	v_fmac_f32_e32 v229, v46, v5
	v_fmac_f32_e32 v228, v31, v6
	v_fmac_f32_e32 v229, v47, v6
	global_load_dwordx4 v[132:135], v1, s[28:29]
	global_load_dwordx4 v[136:139], v1, s[28:29] offset:16
	s_add_u32 s28, s28, 0x80000
	s_addc_u32 s29, s29, 0
	global_load_dwordx4 v[140:143], v1, s[28:29]
	global_load_dwordx4 v[144:147], v1, s[28:29] offset:16
	s_add_u32 s28, s28, 0x80000
	s_addc_u32 s29, s29, 0
	global_load_dwordx4 v[148:151], v1, s[28:29]
	global_load_dwordx4 v[152:155], v1, s[28:29] offset:16
	s_add_u32 s28, s28, 0x80000
	s_addc_u32 s29, s29, 0
	global_load_dwordx4 v[156:159], v1, s[28:29]
	global_load_dwordx4 v[160:163], v1, s[28:29] offset:16
	s_add_u32 s28, s28, 0x80000
	s_addc_u32 s29, s29, 0
	v_add_f32_dpp v212, v212, v212 quad_perm:[1,0,3,2] row_mask:0xf bank_mask:0xf
	v_add_f32_dpp v213, v213, v213 quad_perm:[1,0,3,2] row_mask:0xf bank_mask:0xf
	v_add_f32_dpp v214, v214, v214 quad_perm:[1,0,3,2] row_mask:0xf bank_mask:0xf
	v_add_f32_dpp v215, v215, v215 quad_perm:[1,0,3,2] row_mask:0xf bank_mask:0xf
	v_add_f32_dpp v216, v216, v216 quad_perm:[1,0,3,2] row_mask:0xf bank_mask:0xf
	v_add_f32_dpp v217, v217, v217 quad_perm:[1,0,3,2] row_mask:0xf bank_mask:0xf
	v_add_f32_dpp v218, v218, v218 quad_perm:[1,0,3,2] row_mask:0xf bank_mask:0xf
	v_add_f32_dpp v219, v219, v219 quad_perm:[1,0,3,2] row_mask:0xf bank_mask:0xf
	v_add_f32_dpp v220, v220, v220 quad_perm:[1,0,3,2] row_mask:0xf bank_mask:0xf
	v_add_f32_dpp v221, v221, v221 quad_perm:[1,0,3,2] row_mask:0xf bank_mask:0xf
	v_add_f32_dpp v222, v222, v222 quad_perm:[1,0,3,2] row_mask:0xf bank_mask:0xf
	v_add_f32_dpp v223, v223, v223 quad_perm:[1,0,3,2] row_mask:0xf bank_mask:0xf
	v_add_f32_dpp v224, v224, v224 quad_perm:[1,0,3,2] row_mask:0xf bank_mask:0xf
	v_add_f32_dpp v225, v225, v225 quad_perm:[1,0,3,2] row_mask:0xf bank_mask:0xf
	v_add_f32_dpp v226, v226, v226 quad_perm:[1,0,3,2] row_mask:0xf bank_mask:0xf
	v_add_f32_dpp v227, v227, v227 quad_perm:[1,0,3,2] row_mask:0xf bank_mask:0xf
	v_add_f32_dpp v228, v228, v228 quad_perm:[1,0,3,2] row_mask:0xf bank_mask:0xf
	v_add_f32_dpp v229, v229, v229 quad_perm:[1,0,3,2] row_mask:0xf bank_mask:0xf
	v_add_f32_dpp v212, v212, v212 quad_perm:[2,3,0,1] row_mask:0xf bank_mask:0xf
	v_add_f32_dpp v213, v213, v213 quad_perm:[2,3,0,1] row_mask:0xf bank_mask:0xf
	v_add_f32_dpp v214, v214, v214 quad_perm:[2,3,0,1] row_mask:0xf bank_mask:0xf
	v_add_f32_dpp v215, v215, v215 quad_perm:[2,3,0,1] row_mask:0xf bank_mask:0xf
	v_add_f32_dpp v216, v216, v216 quad_perm:[2,3,0,1] row_mask:0xf bank_mask:0xf
	v_add_f32_dpp v217, v217, v217 quad_perm:[2,3,0,1] row_mask:0xf bank_mask:0xf
	v_add_f32_dpp v218, v218, v218 quad_perm:[2,3,0,1] row_mask:0xf bank_mask:0xf
	v_add_f32_dpp v219, v219, v219 quad_perm:[2,3,0,1] row_mask:0xf bank_mask:0xf
	v_add_f32_dpp v220, v220, v220 quad_perm:[2,3,0,1] row_mask:0xf bank_mask:0xf
	v_add_f32_dpp v221, v221, v221 quad_perm:[2,3,0,1] row_mask:0xf bank_mask:0xf
	v_add_f32_dpp v222, v222, v222 quad_perm:[2,3,0,1] row_mask:0xf bank_mask:0xf
	v_add_f32_dpp v223, v223, v223 quad_perm:[2,3,0,1] row_mask:0xf bank_mask:0xf
	v_add_f32_dpp v224, v224, v224 quad_perm:[2,3,0,1] row_mask:0xf bank_mask:0xf
	v_add_f32_dpp v225, v225, v225 quad_perm:[2,3,0,1] row_mask:0xf bank_mask:0xf
	v_add_f32_dpp v226, v226, v226 quad_perm:[2,3,0,1] row_mask:0xf bank_mask:0xf
	v_add_f32_dpp v227, v227, v227 quad_perm:[2,3,0,1] row_mask:0xf bank_mask:0xf
	v_add_f32_dpp v228, v228, v228 quad_perm:[2,3,0,1] row_mask:0xf bank_mask:0xf
	v_add_f32_dpp v229, v229, v229 quad_perm:[2,3,0,1] row_mask:0xf bank_mask:0xf
	v_add_f32_dpp v212, v212, v212 row_half_mirror row_mask:0xf bank_mask:0xf
	v_add_f32_dpp v213, v213, v213 row_half_mirror row_mask:0xf bank_mask:0xf
	v_add_f32_dpp v214, v214, v214 row_half_mirror row_mask:0xf bank_mask:0xf
	v_add_f32_dpp v215, v215, v215 row_half_mirror row_mask:0xf bank_mask:0xf
	v_add_f32_dpp v216, v216, v216 row_half_mirror row_mask:0xf bank_mask:0xf
	v_add_f32_dpp v217, v217, v217 row_half_mirror row_mask:0xf bank_mask:0xf
	v_add_f32_dpp v218, v218, v218 row_half_mirror row_mask:0xf bank_mask:0xf
	v_add_f32_dpp v219, v219, v219 row_half_mirror row_mask:0xf bank_mask:0xf
	v_add_f32_dpp v220, v220, v220 row_half_mirror row_mask:0xf bank_mask:0xf
	v_add_f32_dpp v221, v221, v221 row_half_mirror row_mask:0xf bank_mask:0xf
	v_add_f32_dpp v222, v222, v222 row_half_mirror row_mask:0xf bank_mask:0xf
	v_add_f32_dpp v223, v223, v223 row_half_mirror row_mask:0xf bank_mask:0xf
	v_add_f32_dpp v224, v224, v224 row_half_mirror row_mask:0xf bank_mask:0xf
	v_add_f32_dpp v225, v225, v225 row_half_mirror row_mask:0xf bank_mask:0xf
	v_add_f32_dpp v226, v226, v226 row_half_mirror row_mask:0xf bank_mask:0xf
	v_add_f32_dpp v227, v227, v227 row_half_mirror row_mask:0xf bank_mask:0xf
	v_add_f32_dpp v228, v228, v228 row_half_mirror row_mask:0xf bank_mask:0xf
	v_add_f32_dpp v229, v229, v229 row_half_mirror row_mask:0xf bank_mask:0xf
	v_add_f32_dpp v212, v212, v212 row_mirror row_mask:0xf bank_mask:0xf
	v_add_f32_dpp v213, v213, v213 row_mirror row_mask:0xf bank_mask:0xf
	v_add_f32_dpp v214, v214, v214 row_mirror row_mask:0xf bank_mask:0xf
	v_add_f32_dpp v215, v215, v215 row_mirror row_mask:0xf bank_mask:0xf
	v_add_f32_dpp v216, v216, v216 row_mirror row_mask:0xf bank_mask:0xf
	v_add_f32_dpp v217, v217, v217 row_mirror row_mask:0xf bank_mask:0xf
	v_add_f32_dpp v218, v218, v218 row_mirror row_mask:0xf bank_mask:0xf
	v_add_f32_dpp v219, v219, v219 row_mirror row_mask:0xf bank_mask:0xf
	v_add_f32_dpp v220, v220, v220 row_mirror row_mask:0xf bank_mask:0xf
	v_add_f32_dpp v221, v221, v221 row_mirror row_mask:0xf bank_mask:0xf
	v_add_f32_dpp v222, v222, v222 row_mirror row_mask:0xf bank_mask:0xf
	v_add_f32_dpp v223, v223, v223 row_mirror row_mask:0xf bank_mask:0xf
	v_add_f32_dpp v224, v224, v224 row_mirror row_mask:0xf bank_mask:0xf
	v_add_f32_dpp v225, v225, v225 row_mirror row_mask:0xf bank_mask:0xf
	v_add_f32_dpp v226, v226, v226 row_mirror row_mask:0xf bank_mask:0xf
	v_add_f32_dpp v227, v227, v227 row_mirror row_mask:0xf bank_mask:0xf
	v_add_f32_dpp v228, v228, v228 row_mirror row_mask:0xf bank_mask:0xf
	v_add_f32_dpp v229, v229, v229 row_mirror row_mask:0xf bank_mask:0xf
	v_add_f32_dpp v212, v212, v212 row_bcast:15 row_mask:0xa bank_mask:0xf
	v_add_f32_dpp v213, v213, v213 row_bcast:15 row_mask:0xa bank_mask:0xf
	v_add_f32_dpp v214, v214, v214 row_bcast:15 row_mask:0xa bank_mask:0xf
	v_add_f32_dpp v215, v215, v215 row_bcast:15 row_mask:0xa bank_mask:0xf
	v_add_f32_dpp v216, v216, v216 row_bcast:15 row_mask:0xa bank_mask:0xf
	v_add_f32_dpp v217, v217, v217 row_bcast:15 row_mask:0xa bank_mask:0xf
	v_add_f32_dpp v218, v218, v218 row_bcast:15 row_mask:0xa bank_mask:0xf
	v_add_f32_dpp v219, v219, v219 row_bcast:15 row_mask:0xa bank_mask:0xf
	v_add_f32_dpp v220, v220, v220 row_bcast:15 row_mask:0xa bank_mask:0xf
	v_add_f32_dpp v221, v221, v221 row_bcast:15 row_mask:0xa bank_mask:0xf
	v_add_f32_dpp v222, v222, v222 row_bcast:15 row_mask:0xa bank_mask:0xf
	v_add_f32_dpp v223, v223, v223 row_bcast:15 row_mask:0xa bank_mask:0xf
	v_add_f32_dpp v224, v224, v224 row_bcast:15 row_mask:0xa bank_mask:0xf
	v_add_f32_dpp v225, v225, v225 row_bcast:15 row_mask:0xa bank_mask:0xf
	v_add_f32_dpp v226, v226, v226 row_bcast:15 row_mask:0xa bank_mask:0xf
	v_add_f32_dpp v227, v227, v227 row_bcast:15 row_mask:0xa bank_mask:0xf
	v_add_f32_dpp v228, v228, v228 row_bcast:15 row_mask:0xa bank_mask:0xf
	v_add_f32_dpp v229, v229, v229 row_bcast:15 row_mask:0xa bank_mask:0xf
	v_add_f32_dpp v212, v212, v212 row_bcast:31 row_mask:0xc bank_mask:0xf
	v_add_f32_dpp v213, v213, v213 row_bcast:31 row_mask:0xc bank_mask:0xf
	v_add_f32_dpp v214, v214, v214 row_bcast:31 row_mask:0xc bank_mask:0xf
	v_add_f32_dpp v215, v215, v215 row_bcast:31 row_mask:0xc bank_mask:0xf
	v_add_f32_dpp v216, v216, v216 row_bcast:31 row_mask:0xc bank_mask:0xf
	v_add_f32_dpp v217, v217, v217 row_bcast:31 row_mask:0xc bank_mask:0xf
	v_add_f32_dpp v218, v218, v218 row_bcast:31 row_mask:0xc bank_mask:0xf
	v_add_f32_dpp v219, v219, v219 row_bcast:31 row_mask:0xc bank_mask:0xf
	v_add_f32_dpp v220, v220, v220 row_bcast:31 row_mask:0xc bank_mask:0xf
	v_add_f32_dpp v221, v221, v221 row_bcast:31 row_mask:0xc bank_mask:0xf
	v_add_f32_dpp v222, v222, v222 row_bcast:31 row_mask:0xc bank_mask:0xf
	v_add_f32_dpp v223, v223, v223 row_bcast:31 row_mask:0xc bank_mask:0xf
	v_add_f32_dpp v224, v224, v224 row_bcast:31 row_mask:0xc bank_mask:0xf
	v_add_f32_dpp v225, v225, v225 row_bcast:31 row_mask:0xc bank_mask:0xf
	v_add_f32_dpp v226, v226, v226 row_bcast:31 row_mask:0xc bank_mask:0xf
	v_add_f32_dpp v227, v227, v227 row_bcast:31 row_mask:0xc bank_mask:0xf
	v_add_f32_dpp v228, v228, v228 row_bcast:31 row_mask:0xc bank_mask:0xf
	v_add_f32_dpp v229, v229, v229 row_bcast:31 row_mask:0xc bank_mask:0xf
	s_nop 0
	v_readlane_b32 s32, v212, 63
	v_readlane_b32 s33, v213, 63
	v_readlane_b32 s40, v214, 63
	v_readlane_b32 s41, v215, 63
	v_readlane_b32 s46, v216, 63
	v_readlane_b32 s47, v217, 63
	v_readlane_b32 s51, v218, 63
	v_readlane_b32 s57, v219, 63
	v_readlane_b32 s58, v220, 63
	v_readlane_b32 s59, v221, 63
	v_readlane_b32 s60, v222, 63
	v_readlane_b32 s61, v223, 63
	v_readlane_b32 s62, v224, 63
	v_readlane_b32 s63, v225, 63
	v_readlane_b32 s70, v226, 63
	v_readlane_b32 s71, v227, 63
	v_readlane_b32 s74, v228, 63
	v_readlane_b32 s75, v229, 63
	s_nop 1
	v_writelane_b32 v9, s32, 0
	v_writelane_b32 v9, s33, 1
	v_writelane_b32 v9, s40, 2
	v_writelane_b32 v9, s41, 3
	v_writelane_b32 v9, s46, 4
	v_writelane_b32 v9, s47, 5
	v_writelane_b32 v9, s51, 6
	v_writelane_b32 v9, s57, 7
	v_writelane_b32 v9, s58, 8
	v_writelane_b32 v9, s59, 9
	v_writelane_b32 v9, s60, 10
	v_writelane_b32 v9, s61, 11
	v_writelane_b32 v9, s62, 12
	v_writelane_b32 v9, s63, 13
	v_writelane_b32 v9, s70, 14
	v_writelane_b32 v9, s71, 15
	v_writelane_b32 v9, s74, 16
	v_writelane_b32 v9, s75, 17
	s_mul_i32 s91, s3, 11264
	s_add_i32 s91, s91, s5
	s_add_i32 s91, s91, 2304
	s_add_u32 s8, s0, 0x3e00000
	s_addc_u32 s9, s1, 0
	v_add_u32_e32 v15, s91, v14
	v_lshlrev_b32_e32 v15, 2, v15
	s_mov_b64 exec, 0x3ffff
	global_store_dword v15, v9, s[8:9]
	s_mov_b64 exec, -1
	s_waitcnt vmcnt(0)
	v_lshlrev_b32_e32 v5, 16, v132
	v_and_b32_e32 v6, 0xffff0000, v132
	v_mul_f32_e32 v212, v16, v5
	v_mul_f32_e32 v213, v32, v5
	v_fmac_f32_e32 v212, v17, v6
	v_fmac_f32_e32 v213, v33, v6
	v_lshlrev_b32_e32 v7, 16, v140
	v_and_b32_e32 v8, 0xffff0000, v140
	v_mul_f32_e32 v214, v16, v7
	v_mul_f32_e32 v215, v32, v7
	v_fmac_f32_e32 v214, v17, v8
	v_fmac_f32_e32 v215, v33, v8
	v_lshlrev_b32_e32 v5, 16, v148
	v_and_b32_e32 v6, 0xffff0000, v148
	v_mul_f32_e32 v216, v16, v5
	v_mul_f32_e32 v217, v32, v5
	v_fmac_f32_e32 v216, v17, v6
	v_fmac_f32_e32 v217, v33, v6
	v_lshlrev_b32_e32 v7, 16, v156
	v_and_b32_e32 v8, 0xffff0000, v156
	v_mul_f32_e32 v218, v16, v7
	v_mul_f32_e32 v219, v32, v7
	v_fmac_f32_e32 v218, v17, v8
	v_fmac_f32_e32 v219, v33, v8
	v_lshlrev_b32_e32 v5, 16, v133
	v_and_b32_e32 v6, 0xffff0000, v133
	v_fmac_f32_e32 v212, v18, v5
	v_fmac_f32_e32 v213, v34, v5
	v_fmac_f32_e32 v212, v19, v6
	v_fmac_f32_e32 v213, v35, v6
	v_lshlrev_b32_e32 v7, 16, v141
	v_and_b32_e32 v8, 0xffff0000, v141
	v_fmac_f32_e32 v214, v18, v7
	v_fmac_f32_e32 v215, v34, v7
	v_fmac_f32_e32 v214, v19, v8
	v_fmac_f32_e32 v215, v35, v8
	v_lshlrev_b32_e32 v5, 16, v149
	v_and_b32_e32 v6, 0xffff0000, v149
	v_fmac_f32_e32 v216, v18, v5
	v_fmac_f32_e32 v217, v34, v5
	v_fmac_f32_e32 v216, v19, v6
	v_fmac_f32_e32 v217, v35, v6
	v_lshlrev_b32_e32 v7, 16, v157
	v_and_b32_e32 v8, 0xffff0000, v157
	v_fmac_f32_e32 v218, v18, v7
	v_fmac_f32_e32 v219, v34, v7
	v_fmac_f32_e32 v218, v19, v8
	v_fmac_f32_e32 v219, v35, v8
	v_lshlrev_b32_e32 v5, 16, v134
	v_and_b32_e32 v6, 0xffff0000, v134
	v_fmac_f32_e32 v212, v20, v5
	v_fmac_f32_e32 v213, v36, v5
	v_fmac_f32_e32 v212, v21, v6
	v_fmac_f32_e32 v213, v37, v6
	v_lshlrev_b32_e32 v7, 16, v142
	v_and_b32_e32 v8, 0xffff0000, v142
	v_fmac_f32_e32 v214, v20, v7
	v_fmac_f32_e32 v215, v36, v7
	v_fmac_f32_e32 v214, v21, v8
	v_fmac_f32_e32 v215, v37, v8
	v_lshlrev_b32_e32 v5, 16, v150
	v_and_b32_e32 v6, 0xffff0000, v150
	v_fmac_f32_e32 v216, v20, v5
	v_fmac_f32_e32 v217, v36, v5
	v_fmac_f32_e32 v216, v21, v6
	v_fmac_f32_e32 v217, v37, v6
	v_lshlrev_b32_e32 v7, 16, v158
	v_and_b32_e32 v8, 0xffff0000, v158
	v_fmac_f32_e32 v218, v20, v7
	v_fmac_f32_e32 v219, v36, v7
	v_fmac_f32_e32 v218, v21, v8
	v_fmac_f32_e32 v219, v37, v8
	v_lshlrev_b32_e32 v5, 16, v135
	v_and_b32_e32 v6, 0xffff0000, v135
	v_fmac_f32_e32 v212, v22, v5
	v_fmac_f32_e32 v213, v38, v5
	v_fmac_f32_e32 v212, v23, v6
	v_fmac_f32_e32 v213, v39, v6
	v_lshlrev_b32_e32 v7, 16, v143
	v_and_b32_e32 v8, 0xffff0000, v143
	v_fmac_f32_e32 v214, v22, v7
	v_fmac_f32_e32 v215, v38, v7
	v_fmac_f32_e32 v214, v23, v8
	v_fmac_f32_e32 v215, v39, v8
	v_lshlrev_b32_e32 v5, 16, v151
	v_and_b32_e32 v6, 0xffff0000, v151
	v_fmac_f32_e32 v216, v22, v5
	v_fmac_f32_e32 v217, v38, v5
	v_fmac_f32_e32 v216, v23, v6
	v_fmac_f32_e32 v217, v39, v6
	v_lshlrev_b32_e32 v7, 16, v159
	v_and_b32_e32 v8, 0xffff0000, v159
	v_fmac_f32_e32 v218, v22, v7
	v_fmac_f32_e32 v219, v38, v7
	v_fmac_f32_e32 v218, v23, v8
	v_fmac_f32_e32 v219, v39, v8
	v_lshlrev_b32_e32 v5, 16, v136
	v_and_b32_e32 v6, 0xffff0000, v136
	v_fmac_f32_e32 v212, v24, v5
	v_fmac_f32_e32 v213, v40, v5
	v_fmac_f32_e32 v212, v25, v6
	v_fmac_f32_e32 v213, v41, v6
	v_lshlrev_b32_e32 v7, 16, v144
	v_and_b32_e32 v8, 0xffff0000, v144
	v_fmac_f32_e32 v214, v24, v7
	v_fmac_f32_e32 v215, v40, v7
	v_fmac_f32_e32 v214, v25, v8
	v_fmac_f32_e32 v215, v41, v8
	v_lshlrev_b32_e32 v5, 16, v152
	v_and_b32_e32 v6, 0xffff0000, v152
	v_fmac_f32_e32 v216, v24, v5
	v_fmac_f32_e32 v217, v40, v5
	v_fmac_f32_e32 v216, v25, v6
	v_fmac_f32_e32 v217, v41, v6
	v_lshlrev_b32_e32 v7, 16, v160
	v_and_b32_e32 v8, 0xffff0000, v160
	v_fmac_f32_e32 v218, v24, v7
	v_fmac_f32_e32 v219, v40, v7
	v_fmac_f32_e32 v218, v25, v8
	v_fmac_f32_e32 v219, v41, v8
	v_lshlrev_b32_e32 v5, 16, v137
	v_and_b32_e32 v6, 0xffff0000, v137
	v_fmac_f32_e32 v212, v26, v5
	v_fmac_f32_e32 v213, v42, v5
	v_fmac_f32_e32 v212, v27, v6
	v_fmac_f32_e32 v213, v43, v6
	v_lshlrev_b32_e32 v7, 16, v145
	v_and_b32_e32 v8, 0xffff0000, v145
	v_fmac_f32_e32 v214, v26, v7
	v_fmac_f32_e32 v215, v42, v7
	v_fmac_f32_e32 v214, v27, v8
	v_fmac_f32_e32 v215, v43, v8
	v_lshlrev_b32_e32 v5, 16, v153
	v_and_b32_e32 v6, 0xffff0000, v153
	v_fmac_f32_e32 v216, v26, v5
	v_fmac_f32_e32 v217, v42, v5
	v_fmac_f32_e32 v216, v27, v6
	v_fmac_f32_e32 v217, v43, v6
	v_lshlrev_b32_e32 v7, 16, v161
	v_and_b32_e32 v8, 0xffff0000, v161
	v_fmac_f32_e32 v218, v26, v7
	v_fmac_f32_e32 v219, v42, v7
	v_fmac_f32_e32 v218, v27, v8
	v_fmac_f32_e32 v219, v43, v8
	v_lshlrev_b32_e32 v5, 16, v138
	v_and_b32_e32 v6, 0xffff0000, v138
	v_fmac_f32_e32 v212, v28, v5
	v_fmac_f32_e32 v213, v44, v5
	v_fmac_f32_e32 v212, v29, v6
	v_fmac_f32_e32 v213, v45, v6
	v_lshlrev_b32_e32 v7, 16, v146
	v_and_b32_e32 v8, 0xffff0000, v146
	v_fmac_f32_e32 v214, v28, v7
	v_fmac_f32_e32 v215, v44, v7
	v_fmac_f32_e32 v214, v29, v8
	v_fmac_f32_e32 v215, v45, v8
	v_lshlrev_b32_e32 v5, 16, v154
	v_and_b32_e32 v6, 0xffff0000, v154
	v_fmac_f32_e32 v216, v28, v5
	v_fmac_f32_e32 v217, v44, v5
	v_fmac_f32_e32 v216, v29, v6
	v_fmac_f32_e32 v217, v45, v6
	v_lshlrev_b32_e32 v7, 16, v162
	v_and_b32_e32 v8, 0xffff0000, v162
	v_fmac_f32_e32 v218, v28, v7
	v_fmac_f32_e32 v219, v44, v7
	v_fmac_f32_e32 v218, v29, v8
	v_fmac_f32_e32 v219, v45, v8
	v_lshlrev_b32_e32 v5, 16, v139
	v_and_b32_e32 v6, 0xffff0000, v139
	v_fmac_f32_e32 v212, v30, v5
	v_fmac_f32_e32 v213, v46, v5
	v_fmac_f32_e32 v212, v31, v6
	v_fmac_f32_e32 v213, v47, v6
	v_lshlrev_b32_e32 v7, 16, v147
	v_and_b32_e32 v8, 0xffff0000, v147
	v_fmac_f32_e32 v214, v30, v7
	v_fmac_f32_e32 v215, v46, v7
	v_fmac_f32_e32 v214, v31, v8
	v_fmac_f32_e32 v215, v47, v8
	v_lshlrev_b32_e32 v5, 16, v155
	v_and_b32_e32 v6, 0xffff0000, v155
	v_fmac_f32_e32 v216, v30, v5
	v_fmac_f32_e32 v217, v46, v5
	v_fmac_f32_e32 v216, v31, v6
	v_fmac_f32_e32 v217, v47, v6
	v_lshlrev_b32_e32 v7, 16, v163
	v_and_b32_e32 v8, 0xffff0000, v163
	v_fmac_f32_e32 v218, v30, v7
	v_fmac_f32_e32 v219, v46, v7
	v_fmac_f32_e32 v218, v31, v8
	v_fmac_f32_e32 v219, v47, v8
	v_add_f32_dpp v212, v212, v212 quad_perm:[1,0,3,2] row_mask:0xf bank_mask:0xf
	v_add_f32_dpp v213, v213, v213 quad_perm:[1,0,3,2] row_mask:0xf bank_mask:0xf
	v_add_f32_dpp v214, v214, v214 quad_perm:[1,0,3,2] row_mask:0xf bank_mask:0xf
	v_add_f32_dpp v215, v215, v215 quad_perm:[1,0,3,2] row_mask:0xf bank_mask:0xf
	v_add_f32_dpp v216, v216, v216 quad_perm:[1,0,3,2] row_mask:0xf bank_mask:0xf
	v_add_f32_dpp v217, v217, v217 quad_perm:[1,0,3,2] row_mask:0xf bank_mask:0xf
	v_add_f32_dpp v218, v218, v218 quad_perm:[1,0,3,2] row_mask:0xf bank_mask:0xf
	v_add_f32_dpp v219, v219, v219 quad_perm:[1,0,3,2] row_mask:0xf bank_mask:0xf
	v_add_f32_dpp v212, v212, v212 quad_perm:[2,3,0,1] row_mask:0xf bank_mask:0xf
	v_add_f32_dpp v213, v213, v213 quad_perm:[2,3,0,1] row_mask:0xf bank_mask:0xf
	v_add_f32_dpp v214, v214, v214 quad_perm:[2,3,0,1] row_mask:0xf bank_mask:0xf
	v_add_f32_dpp v215, v215, v215 quad_perm:[2,3,0,1] row_mask:0xf bank_mask:0xf
	v_add_f32_dpp v216, v216, v216 quad_perm:[2,3,0,1] row_mask:0xf bank_mask:0xf
	v_add_f32_dpp v217, v217, v217 quad_perm:[2,3,0,1] row_mask:0xf bank_mask:0xf
	v_add_f32_dpp v218, v218, v218 quad_perm:[2,3,0,1] row_mask:0xf bank_mask:0xf
	v_add_f32_dpp v219, v219, v219 quad_perm:[2,3,0,1] row_mask:0xf bank_mask:0xf
	v_add_f32_dpp v212, v212, v212 row_half_mirror row_mask:0xf bank_mask:0xf
	v_add_f32_dpp v213, v213, v213 row_half_mirror row_mask:0xf bank_mask:0xf
	v_add_f32_dpp v214, v214, v214 row_half_mirror row_mask:0xf bank_mask:0xf
	v_add_f32_dpp v215, v215, v215 row_half_mirror row_mask:0xf bank_mask:0xf
	v_add_f32_dpp v216, v216, v216 row_half_mirror row_mask:0xf bank_mask:0xf
	v_add_f32_dpp v217, v217, v217 row_half_mirror row_mask:0xf bank_mask:0xf
	v_add_f32_dpp v218, v218, v218 row_half_mirror row_mask:0xf bank_mask:0xf
	v_add_f32_dpp v219, v219, v219 row_half_mirror row_mask:0xf bank_mask:0xf
	v_add_f32_dpp v212, v212, v212 row_mirror row_mask:0xf bank_mask:0xf
	v_add_f32_dpp v213, v213, v213 row_mirror row_mask:0xf bank_mask:0xf
	v_add_f32_dpp v214, v214, v214 row_mirror row_mask:0xf bank_mask:0xf
	v_add_f32_dpp v215, v215, v215 row_mirror row_mask:0xf bank_mask:0xf
	v_add_f32_dpp v216, v216, v216 row_mirror row_mask:0xf bank_mask:0xf
	v_add_f32_dpp v217, v217, v217 row_mirror row_mask:0xf bank_mask:0xf
	v_add_f32_dpp v218, v218, v218 row_mirror row_mask:0xf bank_mask:0xf
	v_add_f32_dpp v219, v219, v219 row_mirror row_mask:0xf bank_mask:0xf
	v_add_f32_dpp v212, v212, v212 row_bcast:15 row_mask:0xa bank_mask:0xf
	v_add_f32_dpp v213, v213, v213 row_bcast:15 row_mask:0xa bank_mask:0xf
	v_add_f32_dpp v214, v214, v214 row_bcast:15 row_mask:0xa bank_mask:0xf
	v_add_f32_dpp v215, v215, v215 row_bcast:15 row_mask:0xa bank_mask:0xf
	v_add_f32_dpp v216, v216, v216 row_bcast:15 row_mask:0xa bank_mask:0xf
	v_add_f32_dpp v217, v217, v217 row_bcast:15 row_mask:0xa bank_mask:0xf
	v_add_f32_dpp v218, v218, v218 row_bcast:15 row_mask:0xa bank_mask:0xf
	v_add_f32_dpp v219, v219, v219 row_bcast:15 row_mask:0xa bank_mask:0xf
	v_add_f32_dpp v212, v212, v212 row_bcast:31 row_mask:0xc bank_mask:0xf
	v_add_f32_dpp v213, v213, v213 row_bcast:31 row_mask:0xc bank_mask:0xf
	v_add_f32_dpp v214, v214, v214 row_bcast:31 row_mask:0xc bank_mask:0xf
	v_add_f32_dpp v215, v215, v215 row_bcast:31 row_mask:0xc bank_mask:0xf
	v_add_f32_dpp v216, v216, v216 row_bcast:31 row_mask:0xc bank_mask:0xf
	v_add_f32_dpp v217, v217, v217 row_bcast:31 row_mask:0xc bank_mask:0xf
	v_add_f32_dpp v218, v218, v218 row_bcast:31 row_mask:0xc bank_mask:0xf
	v_add_f32_dpp v219, v219, v219 row_bcast:31 row_mask:0xc bank_mask:0xf
	s_nop 0
	v_readlane_b32 s32, v212, 63
	v_readlane_b32 s33, v213, 63
	v_readlane_b32 s40, v214, 63
	v_readlane_b32 s41, v215, 63
	v_readlane_b32 s46, v216, 63
	v_readlane_b32 s47, v217, 63
	v_readlane_b32 s51, v218, 63
	v_readlane_b32 s57, v219, 63
	s_nop 1
	v_writelane_b32 v9, s32, 0
	v_writelane_b32 v9, s33, 1
	v_writelane_b32 v9, s40, 2
	v_writelane_b32 v9, s41, 3
	v_writelane_b32 v9, s46, 4
	v_writelane_b32 v9, s47, 5
	v_writelane_b32 v9, s51, 6
	v_writelane_b32 v9, s57, 7
	s_mul_i32 s91, s3, 11264
	s_add_i32 s91, s91, s5
	s_add_i32 s91, s91, 4608
	s_add_u32 s8, s0, 0x3e00000
	s_addc_u32 s9, s1, 0
	v_add_u32_e32 v15, s91, v14
	v_lshlrev_b32_e32 v15, 2, v15
	s_mov_b64 exec, 0xff
	global_store_dword v15, v9, s[8:9]
	s_mov_b64 exec, -1

.Lfastb_1:
	s_waitcnt lgkmcnt(0)
	s_mov_b64 s[4:5], exec
	v_mbcnt_lo_u32_b32 v0, s4, 0
	v_mbcnt_hi_u32_b32 v0, s5, v0
	v_cmp_eq_u32_e32 vcc, 0, v0
	s_waitcnt vmcnt(0)
	buffer_inv sc1
	s_and_saveexec_b64 s[8:9], vcc
	s_cbranch_execz .LBB0_528
	s_bcnt1_i32_b64 s4, s[4:5]
	v_mov_b32_e32 v0, 0x2000
	v_mov_b32_e32 v1, s4
	global_atomic_add v0, v1, s[2:3] offset:1024

.Lfastb_2:
	s_waitcnt lgkmcnt(0)
	s_mov_b64 s[6:7], exec
	v_mbcnt_lo_u32_b32 v0, s6, 0
	v_mbcnt_hi_u32_b32 v0, s7, v0
	v_cmp_eq_u32_e32 vcc, 0, v0
	s_waitcnt vmcnt(0)
	buffer_inv sc1
	s_and_saveexec_b64 s[8:9], vcc
	s_cbranch_execz .LBB0_596
	s_bcnt1_i32_b64 s6, s[6:7]
	v_mov_b32_e32 v0, 0x2000
	v_mov_b32_e32 v1, s6
	global_atomic_add v0, v1, s[2:3] offset:1024

.Lfastb_6:
	s_waitcnt lgkmcnt(0)
	s_mov_b64 s[4:5], exec
	v_mbcnt_lo_u32_b32 v0, s4, 0
	v_mbcnt_hi_u32_b32 v0, s5, v0
	v_cmp_eq_u32_e32 vcc, 0, v0
	s_waitcnt vmcnt(0)
	buffer_inv sc1
	s_and_saveexec_b64 s[6:7], vcc
	s_cbranch_execz .LBB0_1135
	s_bcnt1_i32_b64 s4, s[4:5]
	v_mov_b32_e32 v0, 0x2000
	v_mov_b32_e32 v1, s4
	global_atomic_add v0, v1, s[2:3] offset:1024

.Lfastb_7:
	s_waitcnt lgkmcnt(0)
	s_mov_b64 s[6:7], exec
	v_mbcnt_lo_u32_b32 v0, s6, 0
	v_mbcnt_hi_u32_b32 v0, s7, v0
	v_cmp_eq_u32_e32 vcc, 0, v0
	s_waitcnt vmcnt(0)
	buffer_inv sc1
	s_and_saveexec_b64 s[8:9], vcc
	s_cbranch_execz .LBB0_1233
	s_bcnt1_i32_b64 s6, s[6:7]
	v_mov_b32_e32 v0, 0x2000
	v_mov_b32_e32 v1, s6
	global_atomic_add v0, v1, s[4:5] offset:1024

	.amdhsa_kernel _Z9hymba_fwd4Args
		.amdhsa_group_segment_fixed_size 0
		.amdhsa_private_segment_fixed_size 0
		.amdhsa_kernarg_size 496
		.amdhsa_user_sgpr_count 2
		.amdhsa_user_sgpr_dispatch_ptr 0
		.amdhsa_user_sgpr_queue_ptr 0
		.amdhsa_user_sgpr_kernarg_segment_ptr 1
		.amdhsa_user_sgpr_dispatch_id 0
		.amdhsa_user_sgpr_kernarg_preload_length 0
		.amdhsa_user_sgpr_kernarg_preload_offset 0
		.amdhsa_user_sgpr_private_segment_size 0
		.amdhsa_uses_dynamic_stack 0
		.amdhsa_enable_private_segment 0
		.amdhsa_system_sgpr_workgroup_id_x 1
		.amdhsa_system_sgpr_workgroup_id_y 0
		.amdhsa_system_sgpr_workgroup_id_z 0
		.amdhsa_system_sgpr_workgroup_info 0
		.amdhsa_system_vgpr_workitem_id 2
		.amdhsa_next_free_vgpr 256
		.amdhsa_next_free_sgpr 101
		.amdhsa_accum_offset 256
		.amdhsa_reserve_vcc 1
		.amdhsa_float_round_mode_32 0
		.amdhsa_float_round_mode_16_64 0
		.amdhsa_float_denorm_mode_32 3
		.amdhsa_float_denorm_mode_16_64 3
		.amdhsa_dx10_clamp 1
		.amdhsa_ieee_mode 1
		.amdhsa_fp16_overflow 0
		.amdhsa_tg_split 0
		.amdhsa_exception_fp_ieee_invalid_op 0
		.amdhsa_exception_fp_denorm_src 0
		.amdhsa_exception_fp_ieee_div_zero 0
		.amdhsa_exception_fp_ieee_overflow 0
		.amdhsa_exception_fp_ieee_underflow 0
		.amdhsa_exception_fp_ieee_inexact 0
		.amdhsa_exception_int_div_zero 0
	.end_amdhsa_kernel

amdhsa.kernels:
  - .agpr_count:     0
    .args:
      - .offset:         0
        .size:           240
        .value_kind:     by_value
      - .offset:         240
        .size:           4
        .value_kind:     hidden_block_count_x
      - .offset:         244
        .size:           4
        .value_kind:     hidden_block_count_y
      - .offset:         248
        .size:           4
        .value_kind:     hidden_block_count_z
      - .offset:         252
        .size:           2
        .value_kind:     hidden_group_size_x
      - .offset:         254
        .size:           2
        .value_kind:     hidden_group_size_y
      - .offset:         256
        .size:           2
        .value_kind:     hidden_group_size_z
      - .offset:         258
        .size:           2
        .value_kind:     hidden_remainder_x
      - .offset:         260
        .size:           2
        .value_kind:     hidden_remainder_y
      - .offset:         262
        .size:           2
        .value_kind:     hidden_remainder_z
      - .offset:         280
        .size:           8
        .value_kind:     hidden_global_offset_x
      - .offset:         288
        .size:           8
        .value_kind:     hidden_global_offset_y
      - .offset:         296
        .size:           8
        .value_kind:     hidden_global_offset_z
      - .offset:         304
        .size:           2
        .value_kind:     hidden_grid_dims
      - .offset:         328
        .size:           8
        .value_kind:     hidden_multigrid_sync_arg
      - .offset:         360
        .size:           4
        .value_kind:     hidden_dynamic_lds_size
    .group_segment_fixed_size: 0
    .kernarg_segment_align: 8
    .kernarg_segment_size: 496
    .language:       OpenCL C
    .language_version:
      - 2
      - 0
    .max_flat_workgroup_size: 512
    .name:           _Z9hymba_fwd4Args
    .private_segment_fixed_size: 0
    .sgpr_count:     107
    .sgpr_spill_count: 118
    .symbol:         _Z9hymba_fwd4Args.kd
    .uniform_work_group_size: 1
    .uses_dynamic_stack: false
    .vgpr_count:     256
    .vgpr_spill_count: 0
    .wavefront_size: 64
